# first K iteration of every GEMM tile loop peeled: first-touch matrix instructions take C=0, accumulator zeroing removed from the hot path
# baseline (speedup 1.0000x reference)
.LBB0_202:
	s_andn2_b64 vcc, exec, s[50:51]
	s_cbranch_vccnz .Lcoldzero_1
	s_add_u32 s10, s6, 0x100
	s_addc_u32 s11, s7, 0
	s_add_u32 s6, s8, 0x80
	s_addc_u32 s7, s9, 0
	s_mov_b32 s8, 0
	s_add_i32 s28, s8, 2
	s_add_u32 s29, s6, 0x80
	s_addc_u32 s9, s7, 0
	s_add_i32 s94, 0, 0x10000
	v_add_u32_e32 v138, s94, v141
	ds_read_b128 v[160:163], v138
	ds_read_b128 v[164:167], v138 offset:1024
	ds_read_b128 v[168:171], v138 offset:2048
	ds_read_b128 v[188:191], v138 offset:3072
	s_cmp_eq_u32 s69, s8
	s_cselect_b32 s8, s42, s29
	s_cselect_b32 s9, s43, s9
	s_cselect_b32 s53, s45, s11
	s_cselect_b32 s52, s44, s10
	v_lshl_add_u64 v[138:139], s[6:7], 0, v[136:137]
	s_add_i32 m0, s56, 0xc000
	ds_read_b128 v[192:195], v143
	ds_read_b128 v[196:199], v143 offset:1024
	ds_read_b128 v[200:203], v143 offset:2048
	ds_read_b128 v[204:207], v143 offset:3072
	ds_read_b128 v[208:211], v143 offset:4096
	ds_read_b128 v[212:215], v143 offset:5120
	ds_read_b128 v[216:219], v143 offset:6144
	ds_read_b128 v[220:223], v143 offset:7168
	global_load_lds_dwordx4 v[138:139], off
	v_lshl_add_u64 v[138:139], s[6:7], 0, v[134:135]
	s_add_i32 m0, s56, 0xe000
	s_nop 0
	global_load_lds_dwordx4 v[138:139], off
	s_waitcnt lgkmcnt(8)
	s_barrier
	s_waitcnt lgkmcnt(0)
	s_setprio 1
	v_mfma_f32_16x16x32_bf16 v[120:123], v[160:163], v[192:195], 0
	v_mfma_f32_16x16x32_bf16 v[112:115], v[168:171], v[192:195], 0
	v_mfma_f32_16x16x32_bf16 v[104:107], v[160:163], v[200:203], 0
	v_mfma_f32_16x16x32_bf16 v[96:99], v[168:171], v[200:203], 0
	v_mfma_f32_16x16x32_bf16 v[88:91], v[160:163], v[208:211], 0
	v_mfma_f32_16x16x32_bf16 v[80:83], v[168:171], v[208:211], 0
	v_mfma_f32_16x16x32_bf16 v[72:75], v[160:163], v[216:219], 0
	v_mfma_f32_16x16x32_bf16 v[64:67], v[168:171], v[216:219], 0
	v_mfma_f32_16x16x32_bf16 v[120:123], v[164:167], v[196:199], v[120:123]
	v_mfma_f32_16x16x32_bf16 v[112:115], v[188:191], v[196:199], v[112:115]
	v_mfma_f32_16x16x32_bf16 v[104:107], v[164:167], v[204:207], v[104:107]
	v_mfma_f32_16x16x32_bf16 v[96:99], v[188:191], v[204:207], v[96:99]
	v_mfma_f32_16x16x32_bf16 v[88:91], v[164:167], v[212:215], v[88:91]
	v_mfma_f32_16x16x32_bf16 v[80:83], v[188:191], v[212:215], v[80:83]
	v_mfma_f32_16x16x32_bf16 v[72:75], v[164:167], v[220:223], v[72:75]
	v_mfma_f32_16x16x32_bf16 v[64:67], v[188:191], v[220:223], v[64:67]
	s_setprio 0
	s_barrier
	s_add_i32 s29, 0, 0x14000
	v_add_u32_e32 v138, s29, v141
	s_add_i32 s94, s94, s55
	ds_read_b128 v[224:227], v138
	ds_read_b128 v[228:231], v138 offset:1024
	ds_read_b128 v[232:235], v138 offset:2048
	ds_read_b128 v[236:239], v138 offset:3072
	v_lshl_add_u64 v[138:139], s[52:53], 0, v[144:145]
	s_mov_b32 m0, s94
	v_lshl_add_u64 v[240:241], s[52:53], 0, v[128:129]
	global_load_lds_dwordx4 v[138:139], off
	s_add_i32 m0, s94, 0x2000
	s_nop 0
	global_load_lds_dwordx4 v[240:241], off
	s_barrier
	s_waitcnt lgkmcnt(0)
	s_setprio 1
	v_mfma_f32_16x16x32_bf16 v[124:127], v[224:227], v[192:195], 0
	v_mfma_f32_16x16x32_bf16 v[116:119], v[232:235], v[192:195], 0
	v_mfma_f32_16x16x32_bf16 v[108:111], v[224:227], v[200:203], 0
	v_mfma_f32_16x16x32_bf16 v[100:103], v[232:235], v[200:203], 0
	v_mfma_f32_16x16x32_bf16 v[92:95], v[224:227], v[208:211], 0
	v_mfma_f32_16x16x32_bf16 v[84:87], v[232:235], v[208:211], 0
	v_mfma_f32_16x16x32_bf16 v[76:79], v[224:227], v[216:219], 0
	v_mfma_f32_16x16x32_bf16 v[68:71], v[232:235], v[216:219], 0
	v_mfma_f32_16x16x32_bf16 v[124:127], v[228:231], v[196:199], v[124:127]
	v_mfma_f32_16x16x32_bf16 v[116:119], v[236:239], v[196:199], v[116:119]
	v_mfma_f32_16x16x32_bf16 v[108:111], v[228:231], v[204:207], v[108:111]
	v_mfma_f32_16x16x32_bf16 v[100:103], v[236:239], v[204:207], v[100:103]
	v_mfma_f32_16x16x32_bf16 v[92:95], v[228:231], v[212:215], v[92:95]
	v_mfma_f32_16x16x32_bf16 v[84:87], v[236:239], v[212:215], v[84:87]
	v_mfma_f32_16x16x32_bf16 v[76:79], v[228:231], v[220:223], v[76:79]
	v_mfma_f32_16x16x32_bf16 v[68:71], v[236:239], v[220:223], v[68:71]
	s_setprio 0
	s_mov_b32 m0, s56
	v_lshl_add_u64 v[242:243], s[8:9], 0, v[132:133]
	s_barrier
	ds_read_b128 v[192:195], v143 offset:16384
	ds_read_b128 v[196:199], v143 offset:17408
	ds_read_b128 v[200:203], v143 offset:18432
	ds_read_b128 v[204:207], v143 offset:19456
	ds_read_b128 v[208:211], v143 offset:20480
	ds_read_b128 v[212:215], v143 offset:21504
	ds_read_b128 v[216:219], v143 offset:22528
	ds_read_b128 v[220:223], v143 offset:23552
	global_load_lds_dwordx4 v[242:243], off
	v_lshl_add_u64 v[244:245], s[8:9], 0, v[130:131]
	s_mov_b32 m0, s57
	s_nop 0
	global_load_lds_dwordx4 v[244:245], off
	s_barrier
	s_waitcnt lgkmcnt(0)
	s_setprio 1
	v_mfma_f32_16x16x32_bf16 v[56:59], v[160:163], v[192:195], 0
	v_mfma_f32_16x16x32_bf16 v[48:51], v[168:171], v[192:195], 0
	v_mfma_f32_16x16x32_bf16 v[40:43], v[160:163], v[200:203], 0
	v_mfma_f32_16x16x32_bf16 v[32:35], v[168:171], v[200:203], 0
	v_mfma_f32_16x16x32_bf16 v[24:27], v[160:163], v[208:211], 0
	v_mfma_f32_16x16x32_bf16 v[16:19], v[168:171], v[208:211], 0
	v_mfma_f32_16x16x32_bf16 v[8:11], v[160:163], v[216:219], 0
	v_mfma_f32_16x16x32_bf16 v[0:3], v[168:171], v[216:219], 0
	v_mfma_f32_16x16x32_bf16 v[56:59], v[164:167], v[196:199], v[56:59]
	v_mfma_f32_16x16x32_bf16 v[48:51], v[188:191], v[196:199], v[48:51]
	v_mfma_f32_16x16x32_bf16 v[40:43], v[164:167], v[204:207], v[40:43]
	v_mfma_f32_16x16x32_bf16 v[32:35], v[188:191], v[204:207], v[32:35]
	v_mfma_f32_16x16x32_bf16 v[24:27], v[164:167], v[212:215], v[24:27]
	v_mfma_f32_16x16x32_bf16 v[16:19], v[188:191], v[212:215], v[16:19]
	v_mfma_f32_16x16x32_bf16 v[8:11], v[164:167], v[220:223], v[8:11]
	v_mfma_f32_16x16x32_bf16 v[0:3], v[188:191], v[220:223], v[0:3]
	s_setprio 0
	s_barrier
	s_add_u32 s52, s52, s4
	s_addc_u32 s53, s53, s5
	s_add_i32 s29, s29, s55
	v_lshl_add_u64 v[246:247], s[52:53], 0, v[144:145]
	s_mov_b32 m0, s29
	v_lshl_add_u64 v[248:249], s[52:53], 0, v[128:129]
	global_load_lds_dwordx4 v[246:247], off
	s_add_i32 m0, s29, 0x2000
	s_nop 0
	global_load_lds_dwordx4 v[248:249], off
	s_waitcnt vmcnt(6)
	s_barrier
	s_setprio 1
	v_mfma_f32_16x16x32_bf16 v[60:63], v[224:227], v[192:195], 0
	v_mfma_f32_16x16x32_bf16 v[52:55], v[232:235], v[192:195], 0
	v_mfma_f32_16x16x32_bf16 v[44:47], v[224:227], v[200:203], 0
	v_mfma_f32_16x16x32_bf16 v[36:39], v[232:235], v[200:203], 0
	v_mfma_f32_16x16x32_bf16 v[28:31], v[224:227], v[208:211], 0
	v_mfma_f32_16x16x32_bf16 v[20:23], v[232:235], v[208:211], 0
	v_mfma_f32_16x16x32_bf16 v[12:15], v[224:227], v[216:219], 0
	v_mfma_f32_16x16x32_bf16 v[4:7], v[232:235], v[216:219], 0
	v_mfma_f32_16x16x32_bf16 v[60:63], v[228:231], v[196:199], v[60:63]
	v_mfma_f32_16x16x32_bf16 v[52:55], v[236:239], v[196:199], v[52:55]
	v_mfma_f32_16x16x32_bf16 v[44:47], v[228:231], v[204:207], v[44:47]
	v_mfma_f32_16x16x32_bf16 v[36:39], v[236:239], v[204:207], v[36:39]
	v_mfma_f32_16x16x32_bf16 v[28:31], v[228:231], v[212:215], v[28:31]
	v_mfma_f32_16x16x32_bf16 v[20:23], v[236:239], v[212:215], v[20:23]
	v_mfma_f32_16x16x32_bf16 v[12:15], v[228:231], v[220:223], v[12:15]
	v_mfma_f32_16x16x32_bf16 v[4:7], v[236:239], v[220:223], v[4:7]
	s_setprio 0
	s_add_i32 s29, 0, 0x18000
	v_add_u32_e32 v188, s29, v141
	s_barrier
	ds_read_b128 v[160:163], v188
	ds_read_b128 v[164:167], v188 offset:1024
	ds_read_b128 v[168:171], v188 offset:2048
	ds_read_b128 v[188:191], v188 offset:3072
	s_add_u32 s8, s8, s4
	s_addc_u32 s9, s9, s5
	s_mov_b32 m0, s58
	v_lshl_add_u64 v[224:225], s[8:9], 0, v[132:133]
	ds_read_b128 v[192:195], v143 offset:32768
	ds_read_b128 v[196:199], v143 offset:33792
	ds_read_b128 v[200:203], v143 offset:34816
	ds_read_b128 v[204:207], v143 offset:35840
	ds_read_b128 v[208:211], v143 offset:36864
	ds_read_b128 v[212:215], v143 offset:37888
	ds_read_b128 v[216:219], v143 offset:38912
	ds_read_b128 v[220:223], v143 offset:39936
	global_load_lds_dwordx4 v[224:225], off
	v_lshl_add_u64 v[224:225], s[8:9], 0, v[130:131]
	s_mov_b32 m0, s59
	s_nop 0
	global_load_lds_dwordx4 v[224:225], off
	s_waitcnt lgkmcnt(8)
	s_barrier
	s_waitcnt lgkmcnt(0)
	s_setprio 1
	v_mfma_f32_16x16x32_bf16 v[120:123], v[160:163], v[192:195], v[120:123]
	v_mfma_f32_16x16x32_bf16 v[112:115], v[168:171], v[192:195], v[112:115]
	v_mfma_f32_16x16x32_bf16 v[104:107], v[160:163], v[200:203], v[104:107]
	v_mfma_f32_16x16x32_bf16 v[96:99], v[168:171], v[200:203], v[96:99]
	v_mfma_f32_16x16x32_bf16 v[88:91], v[160:163], v[208:211], v[88:91]
	v_mfma_f32_16x16x32_bf16 v[80:83], v[168:171], v[208:211], v[80:83]
	v_mfma_f32_16x16x32_bf16 v[72:75], v[160:163], v[216:219], v[72:75]
	v_mfma_f32_16x16x32_bf16 v[64:67], v[168:171], v[216:219], v[64:67]
	v_mfma_f32_16x16x32_bf16 v[120:123], v[164:167], v[196:199], v[120:123]
	v_mfma_f32_16x16x32_bf16 v[112:115], v[188:191], v[196:199], v[112:115]
	v_mfma_f32_16x16x32_bf16 v[104:107], v[164:167], v[204:207], v[104:107]
	v_mfma_f32_16x16x32_bf16 v[96:99], v[188:191], v[204:207], v[96:99]
	v_mfma_f32_16x16x32_bf16 v[88:91], v[164:167], v[212:215], v[88:91]
	v_mfma_f32_16x16x32_bf16 v[80:83], v[188:191], v[212:215], v[80:83]
	v_mfma_f32_16x16x32_bf16 v[72:75], v[164:167], v[220:223], v[72:75]
	v_mfma_f32_16x16x32_bf16 v[64:67], v[188:191], v[220:223], v[64:67]
	s_setprio 0
	s_barrier
	s_add_i32 s8, 0, 0x1c000
	s_add_i32 s9, s29, s55
	v_add_u32_e32 v236, s8, v141
	v_lshl_add_u64 v[138:139], v[138:139], 0, s[82:83]
	s_mov_b32 m0, s9
	ds_read_b128 v[224:227], v236
	ds_read_b128 v[228:231], v236 offset:1024
	ds_read_b128 v[232:235], v236 offset:2048
	ds_read_b128 v[236:239], v236 offset:3072
	global_load_lds_dwordx4 v[138:139], off
	v_lshl_add_u64 v[138:139], v[240:241], 0, s[82:83]
	s_add_i32 m0, s9, 0x2000
	s_nop 0
	global_load_lds_dwordx4 v[138:139], off
	s_barrier
	s_waitcnt lgkmcnt(0)
	s_setprio 1
	v_mfma_f32_16x16x32_bf16 v[124:127], v[224:227], v[192:195], v[124:127]
	v_mfma_f32_16x16x32_bf16 v[116:119], v[232:235], v[192:195], v[116:119]
	v_mfma_f32_16x16x32_bf16 v[108:111], v[224:227], v[200:203], v[108:111]
	v_mfma_f32_16x16x32_bf16 v[100:103], v[232:235], v[200:203], v[100:103]
	v_mfma_f32_16x16x32_bf16 v[92:95], v[224:227], v[208:211], v[92:95]
	v_mfma_f32_16x16x32_bf16 v[84:87], v[232:235], v[208:211], v[84:87]
	v_mfma_f32_16x16x32_bf16 v[76:79], v[224:227], v[216:219], v[76:79]
	v_mfma_f32_16x16x32_bf16 v[68:71], v[232:235], v[216:219], v[68:71]
	v_mfma_f32_16x16x32_bf16 v[124:127], v[228:231], v[196:199], v[124:127]
	v_mfma_f32_16x16x32_bf16 v[116:119], v[236:239], v[196:199], v[116:119]
	v_mfma_f32_16x16x32_bf16 v[108:111], v[228:231], v[204:207], v[108:111]
	v_mfma_f32_16x16x32_bf16 v[100:103], v[236:239], v[204:207], v[100:103]
	v_mfma_f32_16x16x32_bf16 v[92:95], v[228:231], v[212:215], v[92:95]
	v_mfma_f32_16x16x32_bf16 v[84:87], v[236:239], v[212:215], v[84:87]
	v_mfma_f32_16x16x32_bf16 v[76:79], v[228:231], v[220:223], v[76:79]
	v_mfma_f32_16x16x32_bf16 v[68:71], v[236:239], v[220:223], v[68:71]
	s_setprio 0
	s_mov_b32 m0, s61
	v_lshl_add_u64 v[138:139], v[242:243], 0, s[82:83]
	s_barrier
	ds_read_b128 v[192:195], v143 offset:49152
	ds_read_b128 v[196:199], v143 offset:50176
	ds_read_b128 v[200:203], v143 offset:51200
	ds_read_b128 v[204:207], v143 offset:52224
	ds_read_b128 v[208:211], v143 offset:53248
	ds_read_b128 v[212:215], v143 offset:54272
	ds_read_b128 v[216:219], v143 offset:55296
	ds_read_b128 v[220:223], v143 offset:56320
	global_load_lds_dwordx4 v[138:139], off
	v_lshl_add_u64 v[138:139], v[244:245], 0, s[82:83]
	s_mov_b32 m0, s68
	s_nop 0
	global_load_lds_dwordx4 v[138:139], off
	s_barrier
	s_waitcnt lgkmcnt(0)
	s_setprio 1
	v_mfma_f32_16x16x32_bf16 v[56:59], v[160:163], v[192:195], v[56:59]
	v_mfma_f32_16x16x32_bf16 v[48:51], v[168:171], v[192:195], v[48:51]
	v_mfma_f32_16x16x32_bf16 v[40:43], v[160:163], v[200:203], v[40:43]
	v_mfma_f32_16x16x32_bf16 v[32:35], v[168:171], v[200:203], v[32:35]
	v_mfma_f32_16x16x32_bf16 v[24:27], v[160:163], v[208:211], v[24:27]
	v_mfma_f32_16x16x32_bf16 v[16:19], v[168:171], v[208:211], v[16:19]
	v_mfma_f32_16x16x32_bf16 v[8:11], v[160:163], v[216:219], v[8:11]
	v_mfma_f32_16x16x32_bf16 v[0:3], v[168:171], v[216:219], v[0:3]
	v_mfma_f32_16x16x32_bf16 v[56:59], v[164:167], v[196:199], v[56:59]
	v_mfma_f32_16x16x32_bf16 v[48:51], v[188:191], v[196:199], v[48:51]
	v_mfma_f32_16x16x32_bf16 v[40:43], v[164:167], v[204:207], v[40:43]
	v_mfma_f32_16x16x32_bf16 v[32:35], v[188:191], v[204:207], v[32:35]
	v_mfma_f32_16x16x32_bf16 v[24:27], v[164:167], v[212:215], v[24:27]
	v_mfma_f32_16x16x32_bf16 v[16:19], v[188:191], v[212:215], v[16:19]
	v_mfma_f32_16x16x32_bf16 v[8:11], v[164:167], v[220:223], v[8:11]
	v_mfma_f32_16x16x32_bf16 v[0:3], v[188:191], v[220:223], v[0:3]
	s_setprio 0
	s_barrier
	s_add_i32 s8, s8, s55
	v_lshl_add_u64 v[138:139], v[246:247], 0, s[82:83]
	s_mov_b32 m0, s8
	s_nop 0
	global_load_lds_dwordx4 v[138:139], off
	v_lshl_add_u64 v[138:139], v[248:249], 0, s[82:83]
	s_add_i32 m0, s8, 0x2000
	s_nop 0
	global_load_lds_dwordx4 v[138:139], off
	s_waitcnt vmcnt(6)
	s_barrier
	s_setprio 1
	v_mfma_f32_16x16x32_bf16 v[60:63], v[224:227], v[192:195], v[60:63]
	v_mfma_f32_16x16x32_bf16 v[52:55], v[232:235], v[192:195], v[52:55]
	v_mfma_f32_16x16x32_bf16 v[44:47], v[224:227], v[200:203], v[44:47]
	v_mfma_f32_16x16x32_bf16 v[36:39], v[232:235], v[200:203], v[36:39]
	v_mfma_f32_16x16x32_bf16 v[28:31], v[224:227], v[208:211], v[28:31]
	v_mfma_f32_16x16x32_bf16 v[20:23], v[232:235], v[208:211], v[20:23]
	v_mfma_f32_16x16x32_bf16 v[12:15], v[224:227], v[216:219], v[12:15]
	v_mfma_f32_16x16x32_bf16 v[4:7], v[232:235], v[216:219], v[4:7]
	v_mfma_f32_16x16x32_bf16 v[60:63], v[228:231], v[196:199], v[60:63]
	v_mfma_f32_16x16x32_bf16 v[52:55], v[236:239], v[196:199], v[52:55]
	v_mfma_f32_16x16x32_bf16 v[44:47], v[228:231], v[204:207], v[44:47]
	v_mfma_f32_16x16x32_bf16 v[36:39], v[236:239], v[204:207], v[36:39]
	v_mfma_f32_16x16x32_bf16 v[28:31], v[228:231], v[212:215], v[28:31]
	v_mfma_f32_16x16x32_bf16 v[20:23], v[236:239], v[212:215], v[20:23]
	v_mfma_f32_16x16x32_bf16 v[12:15], v[228:231], v[220:223], v[12:15]
	v_mfma_f32_16x16x32_bf16 v[4:7], v[236:239], v[220:223], v[4:7]
	s_setprio 0
	s_add_u32 s10, s10, 0x100
	s_addc_u32 s11, s11, 0
	s_add_u32 s6, s6, 0x100
	s_addc_u32 s7, s7, 0
	s_cmp_ge_i32 s28, s60
	s_mov_b32 s8, s28
	s_barrier
	s_cbranch_scc0 .LBB0_204
	s_branch .LBB0_195

.LBB0_275:
	s_andn2_b64 vcc, exec, s[48:49]
	s_cbranch_vccnz .Lcoldzero_2
	s_add_u32 s10, s6, 0x100
	s_addc_u32 s11, s7, 0
	s_add_u32 s6, s8, 0x80
	s_addc_u32 s7, s9, 0
	s_mov_b32 s8, 0
	s_add_i32 s28, s8, 2
	s_add_u32 s29, s6, 0x80
	s_addc_u32 s9, s7, 0
	s_add_i32 s91, 0, 0x10000
	v_add_u32_e32 v142, s91, v189
	ds_read_b128 v[134:137], v142
	ds_read_b128 v[138:141], v142 offset:1024
	ds_read_b128 v[160:163], v142 offset:2048
	ds_read_b128 v[164:167], v142 offset:3072
	s_cmp_eq_u32 s61, s8
	s_cselect_b32 s8, s44, s29
	s_cselect_b32 s9, s45, s9
	s_cselect_b32 s51, s47, s11
	s_cselect_b32 s50, s46, s10
	v_lshl_add_u64 v[142:143], s[6:7], 0, v[132:133]
	s_add_i32 m0, s54, 0xc000
	ds_read_b128 v[168:171], v191
	ds_read_b128 v[192:195], v191 offset:1024
	ds_read_b128 v[196:199], v191 offset:2048
	ds_read_b128 v[200:203], v191 offset:3072
	ds_read_b128 v[204:207], v191 offset:4096
	ds_read_b128 v[208:211], v191 offset:5120
	ds_read_b128 v[212:215], v191 offset:6144
	ds_read_b128 v[216:219], v191 offset:7168
	global_load_lds_dwordx4 v[142:143], off
	v_lshl_add_u64 v[142:143], s[6:7], 0, v[130:131]
	s_add_i32 m0, s54, 0xe000
	s_nop 0
	global_load_lds_dwordx4 v[142:143], off
	s_waitcnt lgkmcnt(8)
	s_barrier
	s_waitcnt lgkmcnt(0)
	s_setprio 1
	v_mfma_f32_16x16x32_bf16 v[124:127], v[134:137], v[168:171], 0
	v_mfma_f32_16x16x32_bf16 v[120:123], v[160:163], v[168:171], 0
	v_mfma_f32_16x16x32_bf16 v[108:111], v[134:137], v[196:199], 0
	v_mfma_f32_16x16x32_bf16 v[104:107], v[160:163], v[196:199], 0
	v_mfma_f32_16x16x32_bf16 v[92:95], v[134:137], v[204:207], 0
	v_mfma_f32_16x16x32_bf16 v[88:91], v[160:163], v[204:207], 0
	v_mfma_f32_16x16x32_bf16 v[76:79], v[134:137], v[212:215], 0
	v_mfma_f32_16x16x32_bf16 v[72:75], v[160:163], v[212:215], 0
	v_mfma_f32_16x16x32_bf16 v[124:127], v[138:141], v[192:195], v[124:127]
	v_mfma_f32_16x16x32_bf16 v[120:123], v[164:167], v[192:195], v[120:123]
	v_mfma_f32_16x16x32_bf16 v[108:111], v[138:141], v[200:203], v[108:111]
	v_mfma_f32_16x16x32_bf16 v[104:107], v[164:167], v[200:203], v[104:107]
	v_mfma_f32_16x16x32_bf16 v[92:95], v[138:141], v[208:211], v[92:95]
	v_mfma_f32_16x16x32_bf16 v[88:91], v[164:167], v[208:211], v[88:91]
	v_mfma_f32_16x16x32_bf16 v[76:79], v[138:141], v[216:219], v[76:79]
	v_mfma_f32_16x16x32_bf16 v[72:75], v[164:167], v[216:219], v[72:75]
	s_setprio 0
	s_barrier
	s_add_i32 s29, 0, 0x14000
	v_add_u32_e32 v142, s29, v189
	s_add_i32 s91, s91, s53
	ds_read_b128 v[220:223], v142
	ds_read_b128 v[224:227], v142 offset:1024
	ds_read_b128 v[228:231], v142 offset:2048
	ds_read_b128 v[232:235], v142 offset:3072
	v_lshl_add_u64 v[142:143], s[50:51], 0, v[144:145]
	s_mov_b32 m0, s91
	v_lshl_add_u64 v[236:237], s[50:51], 0, v[128:129]
	global_load_lds_dwordx4 v[142:143], off
	s_add_i32 m0, s91, 0x2000
	s_nop 0
	global_load_lds_dwordx4 v[236:237], off
	s_barrier
	s_waitcnt lgkmcnt(0)
	s_setprio 1
	v_mfma_f32_16x16x32_bf16 v[116:119], v[220:223], v[168:171], 0
	v_mfma_f32_16x16x32_bf16 v[112:115], v[228:231], v[168:171], 0
	v_mfma_f32_16x16x32_bf16 v[100:103], v[220:223], v[196:199], 0
	v_mfma_f32_16x16x32_bf16 v[96:99], v[228:231], v[196:199], 0
	v_mfma_f32_16x16x32_bf16 v[84:87], v[220:223], v[204:207], 0
	v_mfma_f32_16x16x32_bf16 v[80:83], v[228:231], v[204:207], 0
	v_mfma_f32_16x16x32_bf16 v[68:71], v[220:223], v[212:215], 0
	v_mfma_f32_16x16x32_bf16 v[64:67], v[228:231], v[212:215], 0
	v_mfma_f32_16x16x32_bf16 v[116:119], v[224:227], v[192:195], v[116:119]
	v_mfma_f32_16x16x32_bf16 v[112:115], v[232:235], v[192:195], v[112:115]
	v_mfma_f32_16x16x32_bf16 v[100:103], v[224:227], v[200:203], v[100:103]
	v_mfma_f32_16x16x32_bf16 v[96:99], v[232:235], v[200:203], v[96:99]
	v_mfma_f32_16x16x32_bf16 v[84:87], v[224:227], v[208:211], v[84:87]
	v_mfma_f32_16x16x32_bf16 v[80:83], v[232:235], v[208:211], v[80:83]
	v_mfma_f32_16x16x32_bf16 v[68:71], v[224:227], v[216:219], v[68:71]
	v_mfma_f32_16x16x32_bf16 v[64:67], v[232:235], v[216:219], v[64:67]
	s_setprio 0
	s_mov_b32 m0, s54
	v_lshl_add_u64 v[238:239], s[8:9], 0, v[144:145]
	s_barrier
	ds_read_b128 v[168:171], v191 offset:16384
	ds_read_b128 v[192:195], v191 offset:17408
	ds_read_b128 v[196:199], v191 offset:18432
	ds_read_b128 v[200:203], v191 offset:19456
	ds_read_b128 v[204:207], v191 offset:20480
	ds_read_b128 v[208:211], v191 offset:21504
	ds_read_b128 v[212:215], v191 offset:22528
	ds_read_b128 v[216:219], v191 offset:23552
	global_load_lds_dwordx4 v[238:239], off
	v_lshl_add_u64 v[240:241], s[8:9], 0, v[128:129]
	s_mov_b32 m0, s55
	s_nop 0
	global_load_lds_dwordx4 v[240:241], off
	s_barrier
	s_waitcnt lgkmcnt(0)
	s_setprio 1
	v_mfma_f32_16x16x32_bf16 v[60:63], v[134:137], v[168:171], 0
	v_mfma_f32_16x16x32_bf16 v[56:59], v[160:163], v[168:171], 0
	v_mfma_f32_16x16x32_bf16 v[44:47], v[134:137], v[196:199], 0
	v_mfma_f32_16x16x32_bf16 v[40:43], v[160:163], v[196:199], 0
	v_mfma_f32_16x16x32_bf16 v[28:31], v[134:137], v[204:207], 0
	v_mfma_f32_16x16x32_bf16 v[24:27], v[160:163], v[204:207], 0
	v_mfma_f32_16x16x32_bf16 v[12:15], v[134:137], v[212:215], 0
	v_mfma_f32_16x16x32_bf16 v[8:11], v[160:163], v[212:215], 0
	v_mfma_f32_16x16x32_bf16 v[60:63], v[138:141], v[192:195], v[60:63]
	v_mfma_f32_16x16x32_bf16 v[56:59], v[164:167], v[192:195], v[56:59]
	v_mfma_f32_16x16x32_bf16 v[44:47], v[138:141], v[200:203], v[44:47]
	v_mfma_f32_16x16x32_bf16 v[40:43], v[164:167], v[200:203], v[40:43]
	v_mfma_f32_16x16x32_bf16 v[28:31], v[138:141], v[208:211], v[28:31]
	v_mfma_f32_16x16x32_bf16 v[24:27], v[164:167], v[208:211], v[24:27]
	v_mfma_f32_16x16x32_bf16 v[12:15], v[138:141], v[216:219], v[12:15]
	v_mfma_f32_16x16x32_bf16 v[8:11], v[164:167], v[216:219], v[8:11]
	s_setprio 0
	s_barrier
	s_add_u32 s50, s50, s4
	s_addc_u32 s51, s51, s5
	s_add_i32 s29, s29, s53
	v_lshl_add_u64 v[242:243], s[50:51], 0, v[144:145]
	s_mov_b32 m0, s29
	v_lshl_add_u64 v[244:245], s[50:51], 0, v[128:129]
	global_load_lds_dwordx4 v[242:243], off
	s_add_i32 m0, s29, 0x2000
	s_nop 0
	global_load_lds_dwordx4 v[244:245], off
	s_waitcnt vmcnt(6)
	s_barrier
	s_setprio 1
	v_mfma_f32_16x16x32_bf16 v[52:55], v[220:223], v[168:171], 0
	v_mfma_f32_16x16x32_bf16 v[48:51], v[228:231], v[168:171], 0
	v_mfma_f32_16x16x32_bf16 v[36:39], v[220:223], v[196:199], 0
	v_mfma_f32_16x16x32_bf16 v[32:35], v[228:231], v[196:199], 0
	v_mfma_f32_16x16x32_bf16 v[20:23], v[220:223], v[204:207], 0
	v_mfma_f32_16x16x32_bf16 v[16:19], v[228:231], v[204:207], 0
	v_mfma_f32_16x16x32_bf16 v[4:7], v[220:223], v[212:215], 0
	v_mfma_f32_16x16x32_bf16 v[0:3], v[228:231], v[212:215], 0
	v_mfma_f32_16x16x32_bf16 v[52:55], v[224:227], v[192:195], v[52:55]
	v_mfma_f32_16x16x32_bf16 v[48:51], v[232:235], v[192:195], v[48:51]
	v_mfma_f32_16x16x32_bf16 v[36:39], v[224:227], v[200:203], v[36:39]
	v_mfma_f32_16x16x32_bf16 v[32:35], v[232:235], v[200:203], v[32:35]
	v_mfma_f32_16x16x32_bf16 v[20:23], v[224:227], v[208:211], v[20:23]
	v_mfma_f32_16x16x32_bf16 v[16:19], v[232:235], v[208:211], v[16:19]
	v_mfma_f32_16x16x32_bf16 v[4:7], v[224:227], v[216:219], v[4:7]
	v_mfma_f32_16x16x32_bf16 v[0:3], v[232:235], v[216:219], v[0:3]
	s_setprio 0
	s_add_i32 s29, 0, 0x18000
	v_add_u32_e32 v164, s29, v189
	s_barrier
	ds_read_b128 v[134:137], v164
	ds_read_b128 v[138:141], v164 offset:1024
	ds_read_b128 v[160:163], v164 offset:2048
	ds_read_b128 v[164:167], v164 offset:3072
	s_add_u32 s8, s8, s4
	s_addc_u32 s9, s9, s5
	s_mov_b32 m0, s56
	v_lshl_add_u64 v[220:221], s[8:9], 0, v[144:145]
	ds_read_b128 v[168:171], v191 offset:32768
	ds_read_b128 v[192:195], v191 offset:33792
	ds_read_b128 v[196:199], v191 offset:34816
	ds_read_b128 v[200:203], v191 offset:35840
	ds_read_b128 v[204:207], v191 offset:36864
	ds_read_b128 v[208:211], v191 offset:37888
	ds_read_b128 v[212:215], v191 offset:38912
	ds_read_b128 v[216:219], v191 offset:39936
	global_load_lds_dwordx4 v[220:221], off
	v_lshl_add_u64 v[220:221], s[8:9], 0, v[128:129]
	s_mov_b32 m0, s57
	s_nop 0
	global_load_lds_dwordx4 v[220:221], off
	s_waitcnt lgkmcnt(8)
	s_barrier
	s_waitcnt lgkmcnt(0)
	s_setprio 1
	v_mfma_f32_16x16x32_bf16 v[124:127], v[134:137], v[168:171], v[124:127]
	v_mfma_f32_16x16x32_bf16 v[120:123], v[160:163], v[168:171], v[120:123]
	v_mfma_f32_16x16x32_bf16 v[108:111], v[134:137], v[196:199], v[108:111]
	v_mfma_f32_16x16x32_bf16 v[104:107], v[160:163], v[196:199], v[104:107]
	v_mfma_f32_16x16x32_bf16 v[92:95], v[134:137], v[204:207], v[92:95]
	v_mfma_f32_16x16x32_bf16 v[88:91], v[160:163], v[204:207], v[88:91]
	v_mfma_f32_16x16x32_bf16 v[76:79], v[134:137], v[212:215], v[76:79]
	v_mfma_f32_16x16x32_bf16 v[72:75], v[160:163], v[212:215], v[72:75]
	v_mfma_f32_16x16x32_bf16 v[124:127], v[138:141], v[192:195], v[124:127]
	v_mfma_f32_16x16x32_bf16 v[120:123], v[164:167], v[192:195], v[120:123]
	v_mfma_f32_16x16x32_bf16 v[108:111], v[138:141], v[200:203], v[108:111]
	v_mfma_f32_16x16x32_bf16 v[104:107], v[164:167], v[200:203], v[104:107]
	v_mfma_f32_16x16x32_bf16 v[92:95], v[138:141], v[208:211], v[92:95]
	v_mfma_f32_16x16x32_bf16 v[88:91], v[164:167], v[208:211], v[88:91]
	v_mfma_f32_16x16x32_bf16 v[76:79], v[138:141], v[216:219], v[76:79]
	v_mfma_f32_16x16x32_bf16 v[72:75], v[164:167], v[216:219], v[72:75]
	s_setprio 0
	s_barrier
	s_add_i32 s8, 0, 0x1c000
	s_add_i32 s9, s29, s53
	v_add_u32_e32 v232, s8, v189
	v_lshl_add_u64 v[142:143], v[142:143], 0, s[82:83]
	s_mov_b32 m0, s9
	ds_read_b128 v[220:223], v232
	ds_read_b128 v[224:227], v232 offset:1024
	ds_read_b128 v[228:231], v232 offset:2048
	ds_read_b128 v[232:235], v232 offset:3072
	global_load_lds_dwordx4 v[142:143], off
	v_lshl_add_u64 v[142:143], v[236:237], 0, s[82:83]
	s_add_i32 m0, s9, 0x2000
	s_nop 0
	global_load_lds_dwordx4 v[142:143], off
	s_barrier
	s_waitcnt lgkmcnt(0)
	s_setprio 1
	v_mfma_f32_16x16x32_bf16 v[116:119], v[220:223], v[168:171], v[116:119]
	v_mfma_f32_16x16x32_bf16 v[112:115], v[228:231], v[168:171], v[112:115]
	v_mfma_f32_16x16x32_bf16 v[100:103], v[220:223], v[196:199], v[100:103]
	v_mfma_f32_16x16x32_bf16 v[96:99], v[228:231], v[196:199], v[96:99]
	v_mfma_f32_16x16x32_bf16 v[84:87], v[220:223], v[204:207], v[84:87]
	v_mfma_f32_16x16x32_bf16 v[80:83], v[228:231], v[204:207], v[80:83]
	v_mfma_f32_16x16x32_bf16 v[68:71], v[220:223], v[212:215], v[68:71]
	v_mfma_f32_16x16x32_bf16 v[64:67], v[228:231], v[212:215], v[64:67]
	v_mfma_f32_16x16x32_bf16 v[116:119], v[224:227], v[192:195], v[116:119]
	v_mfma_f32_16x16x32_bf16 v[112:115], v[232:235], v[192:195], v[112:115]
	v_mfma_f32_16x16x32_bf16 v[100:103], v[224:227], v[200:203], v[100:103]
	v_mfma_f32_16x16x32_bf16 v[96:99], v[232:235], v[200:203], v[96:99]
	v_mfma_f32_16x16x32_bf16 v[84:87], v[224:227], v[208:211], v[84:87]
	v_mfma_f32_16x16x32_bf16 v[80:83], v[232:235], v[208:211], v[80:83]
	v_mfma_f32_16x16x32_bf16 v[68:71], v[224:227], v[216:219], v[68:71]
	v_mfma_f32_16x16x32_bf16 v[64:67], v[232:235], v[216:219], v[64:67]
	s_setprio 0
	s_mov_b32 m0, s59
	v_lshl_add_u64 v[142:143], v[238:239], 0, s[82:83]
	s_barrier
	ds_read_b128 v[168:171], v191 offset:49152
	ds_read_b128 v[192:195], v191 offset:50176
	ds_read_b128 v[196:199], v191 offset:51200
	ds_read_b128 v[200:203], v191 offset:52224
	ds_read_b128 v[204:207], v191 offset:53248
	ds_read_b128 v[208:211], v191 offset:54272
	ds_read_b128 v[212:215], v191 offset:55296
	ds_read_b128 v[216:219], v191 offset:56320
	global_load_lds_dwordx4 v[142:143], off
	v_lshl_add_u64 v[142:143], v[240:241], 0, s[82:83]
	s_mov_b32 m0, s60
	s_nop 0
	global_load_lds_dwordx4 v[142:143], off
	s_barrier
	s_waitcnt lgkmcnt(0)
	s_setprio 1
	v_mfma_f32_16x16x32_bf16 v[60:63], v[134:137], v[168:171], v[60:63]
	v_mfma_f32_16x16x32_bf16 v[56:59], v[160:163], v[168:171], v[56:59]
	v_mfma_f32_16x16x32_bf16 v[44:47], v[134:137], v[196:199], v[44:47]
	v_mfma_f32_16x16x32_bf16 v[40:43], v[160:163], v[196:199], v[40:43]
	v_mfma_f32_16x16x32_bf16 v[28:31], v[134:137], v[204:207], v[28:31]
	v_mfma_f32_16x16x32_bf16 v[24:27], v[160:163], v[204:207], v[24:27]
	v_mfma_f32_16x16x32_bf16 v[12:15], v[134:137], v[212:215], v[12:15]
	v_mfma_f32_16x16x32_bf16 v[8:11], v[160:163], v[212:215], v[8:11]
	v_mfma_f32_16x16x32_bf16 v[60:63], v[138:141], v[192:195], v[60:63]
	v_mfma_f32_16x16x32_bf16 v[56:59], v[164:167], v[192:195], v[56:59]
	v_mfma_f32_16x16x32_bf16 v[44:47], v[138:141], v[200:203], v[44:47]
	v_mfma_f32_16x16x32_bf16 v[40:43], v[164:167], v[200:203], v[40:43]
	v_mfma_f32_16x16x32_bf16 v[28:31], v[138:141], v[208:211], v[28:31]
	v_mfma_f32_16x16x32_bf16 v[24:27], v[164:167], v[208:211], v[24:27]
	v_mfma_f32_16x16x32_bf16 v[12:15], v[138:141], v[216:219], v[12:15]
	v_mfma_f32_16x16x32_bf16 v[8:11], v[164:167], v[216:219], v[8:11]
	s_setprio 0
	s_barrier
	s_add_i32 s8, s8, s53
	v_lshl_add_u64 v[134:135], v[242:243], 0, s[82:83]
	s_mov_b32 m0, s8
	s_nop 0
	global_load_lds_dwordx4 v[134:135], off
	v_lshl_add_u64 v[134:135], v[244:245], 0, s[82:83]
	s_add_i32 m0, s8, 0x2000
	s_nop 0
	global_load_lds_dwordx4 v[134:135], off
	s_waitcnt vmcnt(6)
	s_barrier
	s_setprio 1
	v_mfma_f32_16x16x32_bf16 v[52:55], v[220:223], v[168:171], v[52:55]
	v_mfma_f32_16x16x32_bf16 v[48:51], v[228:231], v[168:171], v[48:51]
	v_mfma_f32_16x16x32_bf16 v[36:39], v[220:223], v[196:199], v[36:39]
	v_mfma_f32_16x16x32_bf16 v[32:35], v[228:231], v[196:199], v[32:35]
	v_mfma_f32_16x16x32_bf16 v[20:23], v[220:223], v[204:207], v[20:23]
	v_mfma_f32_16x16x32_bf16 v[16:19], v[228:231], v[204:207], v[16:19]
	v_mfma_f32_16x16x32_bf16 v[4:7], v[220:223], v[212:215], v[4:7]
	v_mfma_f32_16x16x32_bf16 v[0:3], v[228:231], v[212:215], v[0:3]
	v_mfma_f32_16x16x32_bf16 v[52:55], v[224:227], v[192:195], v[52:55]
	v_mfma_f32_16x16x32_bf16 v[48:51], v[232:235], v[192:195], v[48:51]
	v_mfma_f32_16x16x32_bf16 v[36:39], v[224:227], v[200:203], v[36:39]
	v_mfma_f32_16x16x32_bf16 v[32:35], v[232:235], v[200:203], v[32:35]
	v_mfma_f32_16x16x32_bf16 v[20:23], v[224:227], v[208:211], v[20:23]
	v_mfma_f32_16x16x32_bf16 v[16:19], v[232:235], v[208:211], v[16:19]
	v_mfma_f32_16x16x32_bf16 v[4:7], v[224:227], v[216:219], v[4:7]
	v_mfma_f32_16x16x32_bf16 v[0:3], v[232:235], v[216:219], v[0:3]
	s_setprio 0
	s_add_u32 s10, s10, 0x100
	s_addc_u32 s11, s11, 0
	s_add_u32 s6, s6, 0x100
	s_addc_u32 s7, s7, 0
	s_cmp_ge_i32 s28, s58
	s_mov_b32 s8, s28
	s_barrier
	s_cbranch_scc0 .LBB0_277
	s_branch .LBB0_264

.LBB0_403:
	s_andn2_b64 vcc, exec, s[40:41]
	s_cbranch_vccnz .Lcoldzero_3
	s_add_u32 s10, s6, 0x100
	s_addc_u32 s11, s7, 0
	s_add_u32 s6, s8, 0x80
	s_addc_u32 s7, s9, 0
	s_mov_b32 s8, 0
	s_add_i32 s28, s8, 2
	s_add_u32 s29, s6, 0x80
	s_addc_u32 s9, s7, 0
	s_add_i32 s71, 0, 0x10000
	v_add_u32_e32 v142, s71, v139
	ds_read_b128 v[160:163], v142
	ds_read_b128 v[164:167], v142 offset:1024
	ds_read_b128 v[168:171], v142 offset:2048
	ds_read_b128 v[188:191], v142 offset:3072
	s_cmp_eq_u32 s59, s8
	s_cselect_b32 s8, s44, s29
	s_cselect_b32 s9, s45, s9
	s_cselect_b32 s49, s47, s11
	s_cselect_b32 s48, s46, s10
	v_lshl_add_u64 v[142:143], s[6:7], 0, v[136:137]
	s_add_i32 m0, s52, 0xc000
	ds_read_b128 v[192:195], v141
	ds_read_b128 v[196:199], v141 offset:1024
	ds_read_b128 v[200:203], v141 offset:2048
	ds_read_b128 v[204:207], v141 offset:3072
	ds_read_b128 v[208:211], v141 offset:4096
	ds_read_b128 v[212:215], v141 offset:5120
	ds_read_b128 v[216:219], v141 offset:6144
	ds_read_b128 v[220:223], v141 offset:7168
	global_load_lds_dwordx4 v[142:143], off
	v_lshl_add_u64 v[142:143], s[6:7], 0, v[134:135]
	s_add_i32 m0, s52, 0xe000
	s_nop 0
	global_load_lds_dwordx4 v[142:143], off
	s_waitcnt lgkmcnt(8)
	s_barrier
	s_waitcnt lgkmcnt(0)
	s_setprio 1
	v_mfma_f32_16x16x32_bf16 v[120:123], v[160:163], v[192:195], 0
	v_mfma_f32_16x16x32_bf16 v[124:127], v[168:171], v[192:195], 0
	v_mfma_f32_16x16x32_bf16 v[108:111], v[160:163], v[200:203], 0
	v_mfma_f32_16x16x32_bf16 v[104:107], v[168:171], v[200:203], 0
	v_mfma_f32_16x16x32_bf16 v[92:95], v[160:163], v[208:211], 0
	v_mfma_f32_16x16x32_bf16 v[88:91], v[168:171], v[208:211], 0
	v_mfma_f32_16x16x32_bf16 v[76:79], v[160:163], v[216:219], 0
	v_mfma_f32_16x16x32_bf16 v[72:75], v[168:171], v[216:219], 0
	v_mfma_f32_16x16x32_bf16 v[120:123], v[164:167], v[196:199], v[120:123]
	v_mfma_f32_16x16x32_bf16 v[124:127], v[188:191], v[196:199], v[124:127]
	v_mfma_f32_16x16x32_bf16 v[108:111], v[164:167], v[204:207], v[108:111]
	v_mfma_f32_16x16x32_bf16 v[104:107], v[188:191], v[204:207], v[104:107]
	v_mfma_f32_16x16x32_bf16 v[92:95], v[164:167], v[212:215], v[92:95]
	v_mfma_f32_16x16x32_bf16 v[88:91], v[188:191], v[212:215], v[88:91]
	v_mfma_f32_16x16x32_bf16 v[76:79], v[164:167], v[220:223], v[76:79]
	v_mfma_f32_16x16x32_bf16 v[72:75], v[188:191], v[220:223], v[72:75]
	s_setprio 0
	s_barrier
	s_add_i32 s29, 0, 0x14000
	v_add_u32_e32 v142, s29, v139
	s_add_i32 s71, s71, s51
	ds_read_b128 v[224:227], v142
	ds_read_b128 v[228:231], v142 offset:1024
	ds_read_b128 v[232:235], v142 offset:2048
	ds_read_b128 v[236:239], v142 offset:3072
	v_lshl_add_u64 v[142:143], s[48:49], 0, v[144:145]
	s_mov_b32 m0, s71
	v_lshl_add_u64 v[240:241], s[48:49], 0, v[128:129]
	global_load_lds_dwordx4 v[142:143], off
	s_add_i32 m0, s71, 0x2000
	s_nop 0
	global_load_lds_dwordx4 v[240:241], off
	s_barrier
	s_waitcnt lgkmcnt(0)
	s_setprio 1
	v_mfma_f32_16x16x32_bf16 v[116:119], v[224:227], v[192:195], 0
	v_mfma_f32_16x16x32_bf16 v[112:115], v[232:235], v[192:195], 0
	v_mfma_f32_16x16x32_bf16 v[100:103], v[224:227], v[200:203], 0
	v_mfma_f32_16x16x32_bf16 v[96:99], v[232:235], v[200:203], 0
	v_mfma_f32_16x16x32_bf16 v[84:87], v[224:227], v[208:211], 0
	v_mfma_f32_16x16x32_bf16 v[80:83], v[232:235], v[208:211], 0
	v_mfma_f32_16x16x32_bf16 v[68:71], v[224:227], v[216:219], 0
	v_mfma_f32_16x16x32_bf16 v[64:67], v[232:235], v[216:219], 0
	v_mfma_f32_16x16x32_bf16 v[116:119], v[228:231], v[196:199], v[116:119]
	v_mfma_f32_16x16x32_bf16 v[112:115], v[236:239], v[196:199], v[112:115]
	v_mfma_f32_16x16x32_bf16 v[100:103], v[228:231], v[204:207], v[100:103]
	v_mfma_f32_16x16x32_bf16 v[96:99], v[236:239], v[204:207], v[96:99]
	v_mfma_f32_16x16x32_bf16 v[84:87], v[228:231], v[212:215], v[84:87]
	v_mfma_f32_16x16x32_bf16 v[80:83], v[236:239], v[212:215], v[80:83]
	v_mfma_f32_16x16x32_bf16 v[68:71], v[228:231], v[220:223], v[68:71]
	v_mfma_f32_16x16x32_bf16 v[64:67], v[236:239], v[220:223], v[64:67]
	s_setprio 0
	s_mov_b32 m0, s52
	v_lshl_add_u64 v[242:243], s[8:9], 0, v[132:133]
	s_barrier
	ds_read_b128 v[192:195], v141 offset:16384
	ds_read_b128 v[196:199], v141 offset:17408
	ds_read_b128 v[200:203], v141 offset:18432
	ds_read_b128 v[204:207], v141 offset:19456
	ds_read_b128 v[208:211], v141 offset:20480
	ds_read_b128 v[212:215], v141 offset:21504
	ds_read_b128 v[216:219], v141 offset:22528
	ds_read_b128 v[220:223], v141 offset:23552
	global_load_lds_dwordx4 v[242:243], off
	v_lshl_add_u64 v[244:245], s[8:9], 0, v[130:131]
	s_mov_b32 m0, s53
	s_nop 0
	global_load_lds_dwordx4 v[244:245], off
	s_barrier
	s_waitcnt lgkmcnt(0)
	s_setprio 1
	v_mfma_f32_16x16x32_bf16 v[60:63], v[160:163], v[192:195], 0
	v_mfma_f32_16x16x32_bf16 v[56:59], v[168:171], v[192:195], 0
	v_mfma_f32_16x16x32_bf16 v[44:47], v[160:163], v[200:203], 0
	v_mfma_f32_16x16x32_bf16 v[40:43], v[168:171], v[200:203], 0
	v_mfma_f32_16x16x32_bf16 v[28:31], v[160:163], v[208:211], 0
	v_mfma_f32_16x16x32_bf16 v[24:27], v[168:171], v[208:211], 0
	v_mfma_f32_16x16x32_bf16 v[12:15], v[160:163], v[216:219], 0
	v_mfma_f32_16x16x32_bf16 v[8:11], v[168:171], v[216:219], 0
	v_mfma_f32_16x16x32_bf16 v[60:63], v[164:167], v[196:199], v[60:63]
	v_mfma_f32_16x16x32_bf16 v[56:59], v[188:191], v[196:199], v[56:59]
	v_mfma_f32_16x16x32_bf16 v[44:47], v[164:167], v[204:207], v[44:47]
	v_mfma_f32_16x16x32_bf16 v[40:43], v[188:191], v[204:207], v[40:43]
	v_mfma_f32_16x16x32_bf16 v[28:31], v[164:167], v[212:215], v[28:31]
	v_mfma_f32_16x16x32_bf16 v[24:27], v[188:191], v[212:215], v[24:27]
	v_mfma_f32_16x16x32_bf16 v[12:15], v[164:167], v[220:223], v[12:15]
	v_mfma_f32_16x16x32_bf16 v[8:11], v[188:191], v[220:223], v[8:11]
	s_setprio 0
	s_barrier
	s_add_u32 s48, s48, s4
	s_addc_u32 s49, s49, s5
	s_add_i32 s29, s29, s51
	v_lshl_add_u64 v[246:247], s[48:49], 0, v[144:145]
	s_mov_b32 m0, s29
	v_lshl_add_u64 v[248:249], s[48:49], 0, v[128:129]
	global_load_lds_dwordx4 v[246:247], off
	s_add_i32 m0, s29, 0x2000
	s_nop 0
	global_load_lds_dwordx4 v[248:249], off
	s_waitcnt vmcnt(6)
	s_barrier
	s_setprio 1
	v_mfma_f32_16x16x32_bf16 v[52:55], v[224:227], v[192:195], 0
	v_mfma_f32_16x16x32_bf16 v[48:51], v[232:235], v[192:195], 0
	v_mfma_f32_16x16x32_bf16 v[36:39], v[224:227], v[200:203], 0
	v_mfma_f32_16x16x32_bf16 v[32:35], v[232:235], v[200:203], 0
	v_mfma_f32_16x16x32_bf16 v[20:23], v[224:227], v[208:211], 0
	v_mfma_f32_16x16x32_bf16 v[16:19], v[232:235], v[208:211], 0
	v_mfma_f32_16x16x32_bf16 v[4:7], v[224:227], v[216:219], 0
	v_mfma_f32_16x16x32_bf16 v[0:3], v[232:235], v[216:219], 0
	v_mfma_f32_16x16x32_bf16 v[52:55], v[228:231], v[196:199], v[52:55]
	v_mfma_f32_16x16x32_bf16 v[48:51], v[236:239], v[196:199], v[48:51]
	v_mfma_f32_16x16x32_bf16 v[36:39], v[228:231], v[204:207], v[36:39]
	v_mfma_f32_16x16x32_bf16 v[32:35], v[236:239], v[204:207], v[32:35]
	v_mfma_f32_16x16x32_bf16 v[20:23], v[228:231], v[212:215], v[20:23]
	v_mfma_f32_16x16x32_bf16 v[16:19], v[236:239], v[212:215], v[16:19]
	v_mfma_f32_16x16x32_bf16 v[4:7], v[228:231], v[220:223], v[4:7]
	v_mfma_f32_16x16x32_bf16 v[0:3], v[236:239], v[220:223], v[0:3]
	s_setprio 0
	s_add_i32 s29, 0, 0x18000
	v_add_u32_e32 v188, s29, v139
	s_barrier
	ds_read_b128 v[160:163], v188
	ds_read_b128 v[164:167], v188 offset:1024
	ds_read_b128 v[168:171], v188 offset:2048
	ds_read_b128 v[188:191], v188 offset:3072
	s_add_u32 s8, s8, s4
	s_addc_u32 s9, s9, s5
	s_mov_b32 m0, s54
	v_lshl_add_u64 v[224:225], s[8:9], 0, v[132:133]
	ds_read_b128 v[192:195], v141 offset:32768
	ds_read_b128 v[196:199], v141 offset:33792
	ds_read_b128 v[200:203], v141 offset:34816
	ds_read_b128 v[204:207], v141 offset:35840
	ds_read_b128 v[208:211], v141 offset:36864
	ds_read_b128 v[212:215], v141 offset:37888
	ds_read_b128 v[216:219], v141 offset:38912
	ds_read_b128 v[220:223], v141 offset:39936
	global_load_lds_dwordx4 v[224:225], off
	v_lshl_add_u64 v[224:225], s[8:9], 0, v[130:131]
	s_mov_b32 m0, s55
	s_nop 0
	global_load_lds_dwordx4 v[224:225], off
	s_waitcnt lgkmcnt(8)
	s_barrier
	s_waitcnt lgkmcnt(0)
	s_setprio 1
	v_mfma_f32_16x16x32_bf16 v[120:123], v[160:163], v[192:195], v[120:123]
	v_mfma_f32_16x16x32_bf16 v[124:127], v[168:171], v[192:195], v[124:127]
	v_mfma_f32_16x16x32_bf16 v[108:111], v[160:163], v[200:203], v[108:111]
	v_mfma_f32_16x16x32_bf16 v[104:107], v[168:171], v[200:203], v[104:107]
	v_mfma_f32_16x16x32_bf16 v[92:95], v[160:163], v[208:211], v[92:95]
	v_mfma_f32_16x16x32_bf16 v[88:91], v[168:171], v[208:211], v[88:91]
	v_mfma_f32_16x16x32_bf16 v[76:79], v[160:163], v[216:219], v[76:79]
	v_mfma_f32_16x16x32_bf16 v[72:75], v[168:171], v[216:219], v[72:75]
	v_mfma_f32_16x16x32_bf16 v[120:123], v[164:167], v[196:199], v[120:123]
	v_mfma_f32_16x16x32_bf16 v[124:127], v[188:191], v[196:199], v[124:127]
	v_mfma_f32_16x16x32_bf16 v[108:111], v[164:167], v[204:207], v[108:111]
	v_mfma_f32_16x16x32_bf16 v[104:107], v[188:191], v[204:207], v[104:107]
	v_mfma_f32_16x16x32_bf16 v[92:95], v[164:167], v[212:215], v[92:95]
	v_mfma_f32_16x16x32_bf16 v[88:91], v[188:191], v[212:215], v[88:91]
	v_mfma_f32_16x16x32_bf16 v[76:79], v[164:167], v[220:223], v[76:79]
	v_mfma_f32_16x16x32_bf16 v[72:75], v[188:191], v[220:223], v[72:75]
	s_setprio 0
	s_barrier
	s_add_i32 s8, 0, 0x1c000
	s_add_i32 s9, s29, s51
	v_add_u32_e32 v236, s8, v139
	v_lshl_add_u64 v[142:143], v[142:143], 0, s[82:83]
	s_mov_b32 m0, s9
	ds_read_b128 v[224:227], v236
	ds_read_b128 v[228:231], v236 offset:1024
	ds_read_b128 v[232:235], v236 offset:2048
	ds_read_b128 v[236:239], v236 offset:3072
	global_load_lds_dwordx4 v[142:143], off
	v_lshl_add_u64 v[142:143], v[240:241], 0, s[82:83]
	s_add_i32 m0, s9, 0x2000
	s_nop 0
	global_load_lds_dwordx4 v[142:143], off
	s_barrier
	s_waitcnt lgkmcnt(0)
	s_setprio 1
	v_mfma_f32_16x16x32_bf16 v[116:119], v[224:227], v[192:195], v[116:119]
	v_mfma_f32_16x16x32_bf16 v[112:115], v[232:235], v[192:195], v[112:115]
	v_mfma_f32_16x16x32_bf16 v[100:103], v[224:227], v[200:203], v[100:103]
	v_mfma_f32_16x16x32_bf16 v[96:99], v[232:235], v[200:203], v[96:99]
	v_mfma_f32_16x16x32_bf16 v[84:87], v[224:227], v[208:211], v[84:87]
	v_mfma_f32_16x16x32_bf16 v[80:83], v[232:235], v[208:211], v[80:83]
	v_mfma_f32_16x16x32_bf16 v[68:71], v[224:227], v[216:219], v[68:71]
	v_mfma_f32_16x16x32_bf16 v[64:67], v[232:235], v[216:219], v[64:67]
	v_mfma_f32_16x16x32_bf16 v[116:119], v[228:231], v[196:199], v[116:119]
	v_mfma_f32_16x16x32_bf16 v[112:115], v[236:239], v[196:199], v[112:115]
	v_mfma_f32_16x16x32_bf16 v[100:103], v[228:231], v[204:207], v[100:103]
	v_mfma_f32_16x16x32_bf16 v[96:99], v[236:239], v[204:207], v[96:99]
	v_mfma_f32_16x16x32_bf16 v[84:87], v[228:231], v[212:215], v[84:87]
	v_mfma_f32_16x16x32_bf16 v[80:83], v[236:239], v[212:215], v[80:83]
	v_mfma_f32_16x16x32_bf16 v[68:71], v[228:231], v[220:223], v[68:71]
	v_mfma_f32_16x16x32_bf16 v[64:67], v[236:239], v[220:223], v[64:67]
	s_setprio 0
	s_mov_b32 m0, s57
	v_lshl_add_u64 v[142:143], v[242:243], 0, s[82:83]
	s_barrier
	ds_read_b128 v[192:195], v141 offset:49152
	ds_read_b128 v[196:199], v141 offset:50176
	ds_read_b128 v[200:203], v141 offset:51200
	ds_read_b128 v[204:207], v141 offset:52224
	ds_read_b128 v[208:211], v141 offset:53248
	ds_read_b128 v[212:215], v141 offset:54272
	ds_read_b128 v[216:219], v141 offset:55296
	ds_read_b128 v[220:223], v141 offset:56320
	global_load_lds_dwordx4 v[142:143], off
	v_lshl_add_u64 v[142:143], v[244:245], 0, s[82:83]
	s_mov_b32 m0, s58
	s_nop 0
	global_load_lds_dwordx4 v[142:143], off
	s_barrier
	s_waitcnt lgkmcnt(0)
	s_setprio 1
	v_mfma_f32_16x16x32_bf16 v[60:63], v[160:163], v[192:195], v[60:63]
	v_mfma_f32_16x16x32_bf16 v[56:59], v[168:171], v[192:195], v[56:59]
	v_mfma_f32_16x16x32_bf16 v[44:47], v[160:163], v[200:203], v[44:47]
	v_mfma_f32_16x16x32_bf16 v[40:43], v[168:171], v[200:203], v[40:43]
	v_mfma_f32_16x16x32_bf16 v[28:31], v[160:163], v[208:211], v[28:31]
	v_mfma_f32_16x16x32_bf16 v[24:27], v[168:171], v[208:211], v[24:27]
	v_mfma_f32_16x16x32_bf16 v[12:15], v[160:163], v[216:219], v[12:15]
	v_mfma_f32_16x16x32_bf16 v[8:11], v[168:171], v[216:219], v[8:11]
	v_mfma_f32_16x16x32_bf16 v[60:63], v[164:167], v[196:199], v[60:63]
	v_mfma_f32_16x16x32_bf16 v[56:59], v[188:191], v[196:199], v[56:59]
	v_mfma_f32_16x16x32_bf16 v[44:47], v[164:167], v[204:207], v[44:47]
	v_mfma_f32_16x16x32_bf16 v[40:43], v[188:191], v[204:207], v[40:43]
	v_mfma_f32_16x16x32_bf16 v[28:31], v[164:167], v[212:215], v[28:31]
	v_mfma_f32_16x16x32_bf16 v[24:27], v[188:191], v[212:215], v[24:27]
	v_mfma_f32_16x16x32_bf16 v[12:15], v[164:167], v[220:223], v[12:15]
	v_mfma_f32_16x16x32_bf16 v[8:11], v[188:191], v[220:223], v[8:11]
	s_setprio 0
	s_barrier
	s_add_i32 s8, s8, s51
	v_lshl_add_u64 v[142:143], v[246:247], 0, s[82:83]
	s_mov_b32 m0, s8
	s_nop 0
	global_load_lds_dwordx4 v[142:143], off
	v_lshl_add_u64 v[142:143], v[248:249], 0, s[82:83]
	s_add_i32 m0, s8, 0x2000
	s_nop 0
	global_load_lds_dwordx4 v[142:143], off
	s_waitcnt vmcnt(6)
	s_barrier
	s_setprio 1
	v_mfma_f32_16x16x32_bf16 v[52:55], v[224:227], v[192:195], v[52:55]
	v_mfma_f32_16x16x32_bf16 v[48:51], v[232:235], v[192:195], v[48:51]
	v_mfma_f32_16x16x32_bf16 v[36:39], v[224:227], v[200:203], v[36:39]
	v_mfma_f32_16x16x32_bf16 v[32:35], v[232:235], v[200:203], v[32:35]
	v_mfma_f32_16x16x32_bf16 v[20:23], v[224:227], v[208:211], v[20:23]
	v_mfma_f32_16x16x32_bf16 v[16:19], v[232:235], v[208:211], v[16:19]
	v_mfma_f32_16x16x32_bf16 v[4:7], v[224:227], v[216:219], v[4:7]
	v_mfma_f32_16x16x32_bf16 v[0:3], v[232:235], v[216:219], v[0:3]
	v_mfma_f32_16x16x32_bf16 v[52:55], v[228:231], v[196:199], v[52:55]
	v_mfma_f32_16x16x32_bf16 v[48:51], v[236:239], v[196:199], v[48:51]
	v_mfma_f32_16x16x32_bf16 v[36:39], v[228:231], v[204:207], v[36:39]
	v_mfma_f32_16x16x32_bf16 v[32:35], v[236:239], v[204:207], v[32:35]
	v_mfma_f32_16x16x32_bf16 v[20:23], v[228:231], v[212:215], v[20:23]
	v_mfma_f32_16x16x32_bf16 v[16:19], v[236:239], v[212:215], v[16:19]
	v_mfma_f32_16x16x32_bf16 v[4:7], v[228:231], v[220:223], v[4:7]
	v_mfma_f32_16x16x32_bf16 v[0:3], v[236:239], v[220:223], v[0:3]
	s_setprio 0
	s_add_u32 s10, s10, 0x100
	s_addc_u32 s11, s11, 0
	s_add_u32 s6, s6, 0x100
	s_addc_u32 s7, s7, 0
	s_cmp_ge_i32 s28, s56
	s_mov_b32 s8, s28
	s_barrier
	s_cbranch_scc0 .LBB0_405
	s_branch .LBB0_392

.LBB0_933:
	s_andn2_b64 vcc, exec, s[40:41]
	s_cbranch_vccnz .Lcoldzero_5
	s_add_u32 s10, s6, 0x100
	s_addc_u32 s11, s7, 0
	s_add_u32 s6, s8, 0x80
	s_addc_u32 s7, s9, 0
	s_mov_b32 s8, 0
	s_add_i32 s28, s8, 2
	s_add_u32 s29, s6, 0x80
	s_addc_u32 s9, s7, 0
	s_add_i32 s71, 0, 0x10000
	v_add_u32_e32 v140, s71, v189
	ds_read_b128 v[80:83], v140
	ds_read_b128 v[132:135], v140 offset:1024
	ds_read_b128 v[136:139], v140 offset:2048
	ds_read_b128 v[140:143], v140 offset:3072
	s_cmp_eq_u32 s59, s8
	s_cselect_b32 s8, s44, s29
	s_cselect_b32 s9, s45, s9
	s_cselect_b32 s49, s47, s11
	s_cselect_b32 s48, s46, s10
	v_lshl_add_u64 v[170:171], s[6:7], 0, v[164:165]
	s_add_i32 m0, s52, 0xc000
	ds_read_b128 v[166:169], v191
	ds_read_b128 v[192:195], v191 offset:1024
	ds_read_b128 v[196:199], v191 offset:2048
	ds_read_b128 v[200:203], v191 offset:3072
	ds_read_b128 v[204:207], v191 offset:4096
	ds_read_b128 v[208:211], v191 offset:5120
	ds_read_b128 v[212:215], v191 offset:6144
	ds_read_b128 v[216:219], v191 offset:7168
	global_load_lds_dwordx4 v[170:171], off
	v_lshl_add_u64 v[170:171], s[6:7], 0, v[162:163]
	s_add_i32 m0, s52, 0xe000
	s_nop 0
	global_load_lds_dwordx4 v[170:171], off
	s_waitcnt lgkmcnt(8)
	s_barrier
	s_waitcnt lgkmcnt(0)
	s_setprio 1
	v_mfma_f32_16x16x32_bf16 v[128:131], v[80:83], v[166:169], 0
	v_mfma_f32_16x16x32_bf16 v[124:127], v[136:139], v[166:169], 0
	v_mfma_f32_16x16x32_bf16 v[112:115], v[80:83], v[196:199], 0
	v_mfma_f32_16x16x32_bf16 v[108:111], v[136:139], v[196:199], 0
	v_mfma_f32_16x16x32_bf16 v[96:99], v[80:83], v[204:207], 0
	v_mfma_f32_16x16x32_bf16 v[92:95], v[136:139], v[204:207], 0
	v_mfma_f32_16x16x32_bf16 v[76:79], v[80:83], v[212:215], 0
	v_mfma_f32_16x16x32_bf16 v[72:75], v[136:139], v[212:215], 0
	v_mfma_f32_16x16x32_bf16 v[128:131], v[132:135], v[192:195], v[128:131]
	v_mfma_f32_16x16x32_bf16 v[124:127], v[140:143], v[192:195], v[124:127]
	v_mfma_f32_16x16x32_bf16 v[112:115], v[132:135], v[200:203], v[112:115]
	v_mfma_f32_16x16x32_bf16 v[108:111], v[140:143], v[200:203], v[108:111]
	v_mfma_f32_16x16x32_bf16 v[96:99], v[132:135], v[208:211], v[96:99]
	v_mfma_f32_16x16x32_bf16 v[92:95], v[140:143], v[208:211], v[92:95]
	v_mfma_f32_16x16x32_bf16 v[76:79], v[132:135], v[216:219], v[76:79]
	v_mfma_f32_16x16x32_bf16 v[72:75], v[140:143], v[216:219], v[72:75]
	s_setprio 0
	s_barrier
	s_add_i32 s29, 0, 0x14000
	v_add_u32_e32 v170, s29, v189
	s_add_i32 s71, s71, s51
	ds_read_b128 v[220:223], v170
	ds_read_b128 v[224:227], v170 offset:1024
	ds_read_b128 v[228:231], v170 offset:2048
	ds_read_b128 v[232:235], v170 offset:3072
	v_lshl_add_u64 v[170:171], s[48:49], 0, v[144:145]
	s_mov_b32 m0, s71
	v_lshl_add_u64 v[236:237], s[48:49], 0, v[160:161]
	global_load_lds_dwordx4 v[170:171], off
	s_add_i32 m0, s71, 0x2000
	s_nop 0
	global_load_lds_dwordx4 v[236:237], off
	s_barrier
	s_waitcnt lgkmcnt(0)
	s_setprio 1
	v_mfma_f32_16x16x32_bf16 v[120:123], v[220:223], v[166:169], 0
	v_mfma_f32_16x16x32_bf16 v[116:119], v[228:231], v[166:169], 0
	v_mfma_f32_16x16x32_bf16 v[104:107], v[220:223], v[196:199], 0
	v_mfma_f32_16x16x32_bf16 v[100:103], v[228:231], v[196:199], 0
	v_mfma_f32_16x16x32_bf16 v[88:91], v[220:223], v[204:207], 0
	v_mfma_f32_16x16x32_bf16 v[84:87], v[228:231], v[204:207], 0
	v_mfma_f32_16x16x32_bf16 v[68:71], v[220:223], v[212:215], 0
	v_mfma_f32_16x16x32_bf16 v[64:67], v[228:231], v[212:215], 0
	v_mfma_f32_16x16x32_bf16 v[120:123], v[224:227], v[192:195], v[120:123]
	v_mfma_f32_16x16x32_bf16 v[116:119], v[232:235], v[192:195], v[116:119]
	v_mfma_f32_16x16x32_bf16 v[104:107], v[224:227], v[200:203], v[104:107]
	v_mfma_f32_16x16x32_bf16 v[100:103], v[232:235], v[200:203], v[100:103]
	v_mfma_f32_16x16x32_bf16 v[88:91], v[224:227], v[208:211], v[88:91]
	v_mfma_f32_16x16x32_bf16 v[84:87], v[232:235], v[208:211], v[84:87]
	v_mfma_f32_16x16x32_bf16 v[68:71], v[224:227], v[216:219], v[68:71]
	v_mfma_f32_16x16x32_bf16 v[64:67], v[232:235], v[216:219], v[64:67]
	s_setprio 0
	s_mov_b32 m0, s52
	v_lshl_add_u64 v[238:239], s[8:9], 0, v[144:145]
	s_barrier
	ds_read_b128 v[166:169], v191 offset:16384
	ds_read_b128 v[192:195], v191 offset:17408
	ds_read_b128 v[196:199], v191 offset:18432
	ds_read_b128 v[200:203], v191 offset:19456
	ds_read_b128 v[204:207], v191 offset:20480
	ds_read_b128 v[208:211], v191 offset:21504
	ds_read_b128 v[212:215], v191 offset:22528
	ds_read_b128 v[216:219], v191 offset:23552
	global_load_lds_dwordx4 v[238:239], off
	v_lshl_add_u64 v[240:241], s[8:9], 0, v[160:161]
	s_mov_b32 m0, s53
	s_nop 0
	global_load_lds_dwordx4 v[240:241], off
	s_barrier
	s_waitcnt lgkmcnt(0)
	s_setprio 1
	v_mfma_f32_16x16x32_bf16 v[60:63], v[80:83], v[166:169], 0
	v_mfma_f32_16x16x32_bf16 v[56:59], v[136:139], v[166:169], 0
	v_mfma_f32_16x16x32_bf16 v[44:47], v[80:83], v[196:199], 0
	v_mfma_f32_16x16x32_bf16 v[40:43], v[136:139], v[196:199], 0
	v_mfma_f32_16x16x32_bf16 v[28:31], v[80:83], v[204:207], 0
	v_mfma_f32_16x16x32_bf16 v[24:27], v[136:139], v[204:207], 0
	v_mfma_f32_16x16x32_bf16 v[12:15], v[80:83], v[212:215], 0
	v_mfma_f32_16x16x32_bf16 v[8:11], v[136:139], v[212:215], 0
	v_mfma_f32_16x16x32_bf16 v[60:63], v[132:135], v[192:195], v[60:63]
	v_mfma_f32_16x16x32_bf16 v[56:59], v[140:143], v[192:195], v[56:59]
	v_mfma_f32_16x16x32_bf16 v[44:47], v[132:135], v[200:203], v[44:47]
	v_mfma_f32_16x16x32_bf16 v[40:43], v[140:143], v[200:203], v[40:43]
	v_mfma_f32_16x16x32_bf16 v[28:31], v[132:135], v[208:211], v[28:31]
	v_mfma_f32_16x16x32_bf16 v[24:27], v[140:143], v[208:211], v[24:27]
	v_mfma_f32_16x16x32_bf16 v[12:15], v[132:135], v[216:219], v[12:15]
	v_mfma_f32_16x16x32_bf16 v[8:11], v[140:143], v[216:219], v[8:11]
	s_setprio 0
	s_barrier
	s_add_u32 s48, s48, s4
	s_addc_u32 s49, s49, s5
	s_add_i32 s29, s29, s51
	v_lshl_add_u64 v[242:243], s[48:49], 0, v[144:145]
	s_mov_b32 m0, s29
	v_lshl_add_u64 v[244:245], s[48:49], 0, v[160:161]
	global_load_lds_dwordx4 v[242:243], off
	s_add_i32 m0, s29, 0x2000
	s_nop 0
	global_load_lds_dwordx4 v[244:245], off
	s_waitcnt vmcnt(6)
	s_barrier
	s_setprio 1
	v_mfma_f32_16x16x32_bf16 v[52:55], v[220:223], v[166:169], 0
	v_mfma_f32_16x16x32_bf16 v[48:51], v[228:231], v[166:169], 0
	v_mfma_f32_16x16x32_bf16 v[36:39], v[220:223], v[196:199], 0
	v_mfma_f32_16x16x32_bf16 v[32:35], v[228:231], v[196:199], 0
	v_mfma_f32_16x16x32_bf16 v[20:23], v[220:223], v[204:207], 0
	v_mfma_f32_16x16x32_bf16 v[16:19], v[228:231], v[204:207], 0
	v_mfma_f32_16x16x32_bf16 v[4:7], v[220:223], v[212:215], 0
	v_mfma_f32_16x16x32_bf16 v[0:3], v[228:231], v[212:215], 0
	v_mfma_f32_16x16x32_bf16 v[52:55], v[224:227], v[192:195], v[52:55]
	v_mfma_f32_16x16x32_bf16 v[48:51], v[232:235], v[192:195], v[48:51]
	v_mfma_f32_16x16x32_bf16 v[36:39], v[224:227], v[200:203], v[36:39]
	v_mfma_f32_16x16x32_bf16 v[32:35], v[232:235], v[200:203], v[32:35]
	v_mfma_f32_16x16x32_bf16 v[20:23], v[224:227], v[208:211], v[20:23]
	v_mfma_f32_16x16x32_bf16 v[16:19], v[232:235], v[208:211], v[16:19]
	v_mfma_f32_16x16x32_bf16 v[4:7], v[224:227], v[216:219], v[4:7]
	v_mfma_f32_16x16x32_bf16 v[0:3], v[232:235], v[216:219], v[0:3]
	s_setprio 0
	s_add_i32 s29, 0, 0x18000
	v_add_u32_e32 v140, s29, v189
	s_barrier
	ds_read_b128 v[80:83], v140
	ds_read_b128 v[132:135], v140 offset:1024
	ds_read_b128 v[136:139], v140 offset:2048
	ds_read_b128 v[140:143], v140 offset:3072
	s_add_u32 s8, s8, s4
	s_addc_u32 s9, s9, s5
	s_mov_b32 m0, s54
	v_lshl_add_u64 v[220:221], s[8:9], 0, v[144:145]
	ds_read_b128 v[166:169], v191 offset:32768
	ds_read_b128 v[192:195], v191 offset:33792
	ds_read_b128 v[196:199], v191 offset:34816
	ds_read_b128 v[200:203], v191 offset:35840
	ds_read_b128 v[204:207], v191 offset:36864
	ds_read_b128 v[208:211], v191 offset:37888
	ds_read_b128 v[212:215], v191 offset:38912
	ds_read_b128 v[216:219], v191 offset:39936
	global_load_lds_dwordx4 v[220:221], off
	v_lshl_add_u64 v[220:221], s[8:9], 0, v[160:161]
	s_mov_b32 m0, s55
	s_nop 0
	global_load_lds_dwordx4 v[220:221], off
	s_waitcnt lgkmcnt(8)
	s_barrier
	s_waitcnt lgkmcnt(0)
	s_setprio 1
	v_mfma_f32_16x16x32_bf16 v[128:131], v[80:83], v[166:169], v[128:131]
	v_mfma_f32_16x16x32_bf16 v[124:127], v[136:139], v[166:169], v[124:127]
	v_mfma_f32_16x16x32_bf16 v[112:115], v[80:83], v[196:199], v[112:115]
	v_mfma_f32_16x16x32_bf16 v[108:111], v[136:139], v[196:199], v[108:111]
	v_mfma_f32_16x16x32_bf16 v[96:99], v[80:83], v[204:207], v[96:99]
	v_mfma_f32_16x16x32_bf16 v[92:95], v[136:139], v[204:207], v[92:95]
	v_mfma_f32_16x16x32_bf16 v[76:79], v[80:83], v[212:215], v[76:79]
	v_mfma_f32_16x16x32_bf16 v[72:75], v[136:139], v[212:215], v[72:75]
	v_mfma_f32_16x16x32_bf16 v[128:131], v[132:135], v[192:195], v[128:131]
	v_mfma_f32_16x16x32_bf16 v[124:127], v[140:143], v[192:195], v[124:127]
	v_mfma_f32_16x16x32_bf16 v[112:115], v[132:135], v[200:203], v[112:115]
	v_mfma_f32_16x16x32_bf16 v[108:111], v[140:143], v[200:203], v[108:111]
	v_mfma_f32_16x16x32_bf16 v[96:99], v[132:135], v[208:211], v[96:99]
	v_mfma_f32_16x16x32_bf16 v[92:95], v[140:143], v[208:211], v[92:95]
	v_mfma_f32_16x16x32_bf16 v[76:79], v[132:135], v[216:219], v[76:79]
	v_mfma_f32_16x16x32_bf16 v[72:75], v[140:143], v[216:219], v[72:75]
	s_setprio 0
	s_barrier
	s_add_i32 s8, 0, 0x1c000
	s_add_i32 s9, s29, s51
	v_add_u32_e32 v232, s8, v189
	v_lshl_add_u64 v[170:171], v[170:171], 0, s[82:83]
	s_mov_b32 m0, s9
	ds_read_b128 v[220:223], v232
	ds_read_b128 v[224:227], v232 offset:1024
	ds_read_b128 v[228:231], v232 offset:2048
	ds_read_b128 v[232:235], v232 offset:3072
	global_load_lds_dwordx4 v[170:171], off
	v_lshl_add_u64 v[170:171], v[236:237], 0, s[82:83]
	s_add_i32 m0, s9, 0x2000
	s_nop 0
	global_load_lds_dwordx4 v[170:171], off
	s_barrier
	s_waitcnt lgkmcnt(0)
	s_setprio 1
	v_mfma_f32_16x16x32_bf16 v[120:123], v[220:223], v[166:169], v[120:123]
	v_mfma_f32_16x16x32_bf16 v[116:119], v[228:231], v[166:169], v[116:119]
	v_mfma_f32_16x16x32_bf16 v[104:107], v[220:223], v[196:199], v[104:107]
	v_mfma_f32_16x16x32_bf16 v[100:103], v[228:231], v[196:199], v[100:103]
	v_mfma_f32_16x16x32_bf16 v[88:91], v[220:223], v[204:207], v[88:91]
	v_mfma_f32_16x16x32_bf16 v[84:87], v[228:231], v[204:207], v[84:87]
	v_mfma_f32_16x16x32_bf16 v[68:71], v[220:223], v[212:215], v[68:71]
	v_mfma_f32_16x16x32_bf16 v[64:67], v[228:231], v[212:215], v[64:67]
	v_mfma_f32_16x16x32_bf16 v[120:123], v[224:227], v[192:195], v[120:123]
	v_mfma_f32_16x16x32_bf16 v[116:119], v[232:235], v[192:195], v[116:119]
	v_mfma_f32_16x16x32_bf16 v[104:107], v[224:227], v[200:203], v[104:107]
	v_mfma_f32_16x16x32_bf16 v[100:103], v[232:235], v[200:203], v[100:103]
	v_mfma_f32_16x16x32_bf16 v[88:91], v[224:227], v[208:211], v[88:91]
	v_mfma_f32_16x16x32_bf16 v[84:87], v[232:235], v[208:211], v[84:87]
	v_mfma_f32_16x16x32_bf16 v[68:71], v[224:227], v[216:219], v[68:71]
	v_mfma_f32_16x16x32_bf16 v[64:67], v[232:235], v[216:219], v[64:67]
	s_setprio 0
	s_mov_b32 m0, s57
	v_lshl_add_u64 v[170:171], v[238:239], 0, s[82:83]
	s_barrier
	ds_read_b128 v[166:169], v191 offset:49152
	ds_read_b128 v[192:195], v191 offset:50176
	ds_read_b128 v[196:199], v191 offset:51200
	ds_read_b128 v[200:203], v191 offset:52224
	ds_read_b128 v[204:207], v191 offset:53248
	ds_read_b128 v[208:211], v191 offset:54272
	ds_read_b128 v[212:215], v191 offset:55296
	ds_read_b128 v[216:219], v191 offset:56320
	global_load_lds_dwordx4 v[170:171], off
	v_lshl_add_u64 v[170:171], v[240:241], 0, s[82:83]
	s_mov_b32 m0, s58
	s_nop 0
	global_load_lds_dwordx4 v[170:171], off
	s_barrier
	s_waitcnt lgkmcnt(0)
	s_setprio 1
	v_mfma_f32_16x16x32_bf16 v[60:63], v[80:83], v[166:169], v[60:63]
	v_mfma_f32_16x16x32_bf16 v[56:59], v[136:139], v[166:169], v[56:59]
	v_mfma_f32_16x16x32_bf16 v[44:47], v[80:83], v[196:199], v[44:47]
	v_mfma_f32_16x16x32_bf16 v[40:43], v[136:139], v[196:199], v[40:43]
	v_mfma_f32_16x16x32_bf16 v[28:31], v[80:83], v[204:207], v[28:31]
	v_mfma_f32_16x16x32_bf16 v[24:27], v[136:139], v[204:207], v[24:27]
	v_mfma_f32_16x16x32_bf16 v[12:15], v[80:83], v[212:215], v[12:15]
	v_mfma_f32_16x16x32_bf16 v[8:11], v[136:139], v[212:215], v[8:11]
	v_mfma_f32_16x16x32_bf16 v[60:63], v[132:135], v[192:195], v[60:63]
	v_mfma_f32_16x16x32_bf16 v[56:59], v[140:143], v[192:195], v[56:59]
	v_mfma_f32_16x16x32_bf16 v[44:47], v[132:135], v[200:203], v[44:47]
	v_mfma_f32_16x16x32_bf16 v[40:43], v[140:143], v[200:203], v[40:43]
	v_mfma_f32_16x16x32_bf16 v[28:31], v[132:135], v[208:211], v[28:31]
	v_mfma_f32_16x16x32_bf16 v[24:27], v[140:143], v[208:211], v[24:27]
	v_mfma_f32_16x16x32_bf16 v[12:15], v[132:135], v[216:219], v[12:15]
	v_mfma_f32_16x16x32_bf16 v[8:11], v[140:143], v[216:219], v[8:11]
	s_setprio 0
	s_barrier
	s_add_i32 s8, s8, s51
	v_lshl_add_u64 v[80:81], v[242:243], 0, s[82:83]
	s_mov_b32 m0, s8
	s_nop 0
	global_load_lds_dwordx4 v[80:81], off
	v_lshl_add_u64 v[80:81], v[244:245], 0, s[82:83]
	s_add_i32 m0, s8, 0x2000
	s_nop 0
	global_load_lds_dwordx4 v[80:81], off
	s_waitcnt vmcnt(6)
	s_barrier
	s_setprio 1
	v_mfma_f32_16x16x32_bf16 v[52:55], v[220:223], v[166:169], v[52:55]
	v_mfma_f32_16x16x32_bf16 v[48:51], v[228:231], v[166:169], v[48:51]
	v_mfma_f32_16x16x32_bf16 v[36:39], v[220:223], v[196:199], v[36:39]
	v_mfma_f32_16x16x32_bf16 v[32:35], v[228:231], v[196:199], v[32:35]
	v_mfma_f32_16x16x32_bf16 v[20:23], v[220:223], v[204:207], v[20:23]
	v_mfma_f32_16x16x32_bf16 v[16:19], v[228:231], v[204:207], v[16:19]
	v_mfma_f32_16x16x32_bf16 v[4:7], v[220:223], v[212:215], v[4:7]
	v_mfma_f32_16x16x32_bf16 v[0:3], v[228:231], v[212:215], v[0:3]
	v_mfma_f32_16x16x32_bf16 v[52:55], v[224:227], v[192:195], v[52:55]
	v_mfma_f32_16x16x32_bf16 v[48:51], v[232:235], v[192:195], v[48:51]
	v_mfma_f32_16x16x32_bf16 v[36:39], v[224:227], v[200:203], v[36:39]
	v_mfma_f32_16x16x32_bf16 v[32:35], v[232:235], v[200:203], v[32:35]
	v_mfma_f32_16x16x32_bf16 v[20:23], v[224:227], v[208:211], v[20:23]
	v_mfma_f32_16x16x32_bf16 v[16:19], v[232:235], v[208:211], v[16:19]
	v_mfma_f32_16x16x32_bf16 v[4:7], v[224:227], v[216:219], v[4:7]
	v_mfma_f32_16x16x32_bf16 v[0:3], v[232:235], v[216:219], v[0:3]
	s_setprio 0
	s_add_u32 s10, s10, 0x100
	s_addc_u32 s11, s11, 0
	s_add_u32 s6, s6, 0x100
	s_addc_u32 s7, s7, 0
	s_cmp_ge_i32 s28, s56
	s_mov_b32 s8, s28
	s_barrier
	s_cbranch_scc0 .LBB0_935
	s_branch .LBB0_922

.LBB0_1057:
	s_andn2_b64 vcc, exec, s[46:47]
	s_cbranch_vccnz .Lcoldzero_6
	s_add_u32 s10, s6, 0x100
	s_addc_u32 s11, s7, 0
	s_add_u32 s6, s8, 0x80
	s_addc_u32 s7, s9, 0
	s_mov_b32 s8, 0
	s_add_i32 s28, s8, 2
	s_add_u32 s29, s6, 0x80
	s_addc_u32 s9, s7, 0
	s_add_i32 s71, 0, 0x10000
	v_add_u32_e32 v138, s71, v141
	ds_read_b128 v[160:163], v138
	ds_read_b128 v[164:167], v138 offset:1024
	ds_read_b128 v[168:171], v138 offset:2048
	ds_read_b128 v[188:191], v138 offset:3072
	s_cmp_eq_u32 s59, s8
	s_cselect_b32 s8, s42, s29
	s_cselect_b32 s9, s43, s9
	s_cselect_b32 s49, s45, s11
	s_cselect_b32 s48, s44, s10
	v_lshl_add_u64 v[138:139], s[6:7], 0, v[136:137]
	s_add_i32 m0, s52, 0xc000
	ds_read_b128 v[192:195], v143
	ds_read_b128 v[196:199], v143 offset:1024
	ds_read_b128 v[200:203], v143 offset:2048
	ds_read_b128 v[204:207], v143 offset:3072
	ds_read_b128 v[208:211], v143 offset:4096
	ds_read_b128 v[212:215], v143 offset:5120
	ds_read_b128 v[216:219], v143 offset:6144
	ds_read_b128 v[220:223], v143 offset:7168
	global_load_lds_dwordx4 v[138:139], off
	v_lshl_add_u64 v[138:139], s[6:7], 0, v[134:135]
	s_add_i32 m0, s52, 0xe000
	s_nop 0
	global_load_lds_dwordx4 v[138:139], off
	s_waitcnt lgkmcnt(8)
	s_barrier
	s_waitcnt lgkmcnt(0)
	s_setprio 1
	v_mfma_f32_16x16x32_bf16 v[120:123], v[160:163], v[192:195], 0
	v_mfma_f32_16x16x32_bf16 v[112:115], v[168:171], v[192:195], 0
	v_mfma_f32_16x16x32_bf16 v[104:107], v[160:163], v[200:203], 0
	v_mfma_f32_16x16x32_bf16 v[96:99], v[168:171], v[200:203], 0
	v_mfma_f32_16x16x32_bf16 v[88:91], v[160:163], v[208:211], 0
	v_mfma_f32_16x16x32_bf16 v[80:83], v[168:171], v[208:211], 0
	v_mfma_f32_16x16x32_bf16 v[72:75], v[160:163], v[216:219], 0
	v_mfma_f32_16x16x32_bf16 v[64:67], v[168:171], v[216:219], 0
	v_mfma_f32_16x16x32_bf16 v[120:123], v[164:167], v[196:199], v[120:123]
	v_mfma_f32_16x16x32_bf16 v[112:115], v[188:191], v[196:199], v[112:115]
	v_mfma_f32_16x16x32_bf16 v[104:107], v[164:167], v[204:207], v[104:107]
	v_mfma_f32_16x16x32_bf16 v[96:99], v[188:191], v[204:207], v[96:99]
	v_mfma_f32_16x16x32_bf16 v[88:91], v[164:167], v[212:215], v[88:91]
	v_mfma_f32_16x16x32_bf16 v[80:83], v[188:191], v[212:215], v[80:83]
	v_mfma_f32_16x16x32_bf16 v[72:75], v[164:167], v[220:223], v[72:75]
	v_mfma_f32_16x16x32_bf16 v[64:67], v[188:191], v[220:223], v[64:67]
	s_setprio 0
	s_barrier
	s_add_i32 s29, 0, 0x14000
	v_add_u32_e32 v138, s29, v141
	s_add_i32 s71, s71, s51
	ds_read_b128 v[224:227], v138
	ds_read_b128 v[228:231], v138 offset:1024
	ds_read_b128 v[232:235], v138 offset:2048
	ds_read_b128 v[236:239], v138 offset:3072
	v_lshl_add_u64 v[138:139], s[48:49], 0, v[144:145]
	s_mov_b32 m0, s71
	v_lshl_add_u64 v[240:241], s[48:49], 0, v[128:129]
	global_load_lds_dwordx4 v[138:139], off
	s_add_i32 m0, s71, 0x2000
	s_nop 0
	global_load_lds_dwordx4 v[240:241], off
	s_barrier
	s_waitcnt lgkmcnt(0)
	s_setprio 1
	v_mfma_f32_16x16x32_bf16 v[124:127], v[224:227], v[192:195], 0
	v_mfma_f32_16x16x32_bf16 v[116:119], v[232:235], v[192:195], 0
	v_mfma_f32_16x16x32_bf16 v[108:111], v[224:227], v[200:203], 0
	v_mfma_f32_16x16x32_bf16 v[100:103], v[232:235], v[200:203], 0
	v_mfma_f32_16x16x32_bf16 v[92:95], v[224:227], v[208:211], 0
	v_mfma_f32_16x16x32_bf16 v[84:87], v[232:235], v[208:211], 0
	v_mfma_f32_16x16x32_bf16 v[76:79], v[224:227], v[216:219], 0
	v_mfma_f32_16x16x32_bf16 v[68:71], v[232:235], v[216:219], 0
	v_mfma_f32_16x16x32_bf16 v[124:127], v[228:231], v[196:199], v[124:127]
	v_mfma_f32_16x16x32_bf16 v[116:119], v[236:239], v[196:199], v[116:119]
	v_mfma_f32_16x16x32_bf16 v[108:111], v[228:231], v[204:207], v[108:111]
	v_mfma_f32_16x16x32_bf16 v[100:103], v[236:239], v[204:207], v[100:103]
	v_mfma_f32_16x16x32_bf16 v[92:95], v[228:231], v[212:215], v[92:95]
	v_mfma_f32_16x16x32_bf16 v[84:87], v[236:239], v[212:215], v[84:87]
	v_mfma_f32_16x16x32_bf16 v[76:79], v[228:231], v[220:223], v[76:79]
	v_mfma_f32_16x16x32_bf16 v[68:71], v[236:239], v[220:223], v[68:71]
	s_setprio 0
	s_mov_b32 m0, s52
	v_lshl_add_u64 v[242:243], s[8:9], 0, v[132:133]
	s_barrier
	ds_read_b128 v[192:195], v143 offset:16384
	ds_read_b128 v[196:199], v143 offset:17408
	ds_read_b128 v[200:203], v143 offset:18432
	ds_read_b128 v[204:207], v143 offset:19456
	ds_read_b128 v[208:211], v143 offset:20480
	ds_read_b128 v[212:215], v143 offset:21504
	ds_read_b128 v[216:219], v143 offset:22528
	ds_read_b128 v[220:223], v143 offset:23552
	global_load_lds_dwordx4 v[242:243], off
	v_lshl_add_u64 v[244:245], s[8:9], 0, v[130:131]
	s_mov_b32 m0, s53
	s_nop 0
	global_load_lds_dwordx4 v[244:245], off
	s_barrier
	s_waitcnt lgkmcnt(0)
	s_setprio 1
	v_mfma_f32_16x16x32_bf16 v[56:59], v[160:163], v[192:195], 0
	v_mfma_f32_16x16x32_bf16 v[48:51], v[168:171], v[192:195], 0
	v_mfma_f32_16x16x32_bf16 v[40:43], v[160:163], v[200:203], 0
	v_mfma_f32_16x16x32_bf16 v[32:35], v[168:171], v[200:203], 0
	v_mfma_f32_16x16x32_bf16 v[24:27], v[160:163], v[208:211], 0
	v_mfma_f32_16x16x32_bf16 v[16:19], v[168:171], v[208:211], 0
	v_mfma_f32_16x16x32_bf16 v[8:11], v[160:163], v[216:219], 0
	v_mfma_f32_16x16x32_bf16 v[0:3], v[168:171], v[216:219], 0
	v_mfma_f32_16x16x32_bf16 v[56:59], v[164:167], v[196:199], v[56:59]
	v_mfma_f32_16x16x32_bf16 v[48:51], v[188:191], v[196:199], v[48:51]
	v_mfma_f32_16x16x32_bf16 v[40:43], v[164:167], v[204:207], v[40:43]
	v_mfma_f32_16x16x32_bf16 v[32:35], v[188:191], v[204:207], v[32:35]
	v_mfma_f32_16x16x32_bf16 v[24:27], v[164:167], v[212:215], v[24:27]
	v_mfma_f32_16x16x32_bf16 v[16:19], v[188:191], v[212:215], v[16:19]
	v_mfma_f32_16x16x32_bf16 v[8:11], v[164:167], v[220:223], v[8:11]
	v_mfma_f32_16x16x32_bf16 v[0:3], v[188:191], v[220:223], v[0:3]
	s_setprio 0
	s_barrier
	s_add_u32 s48, s48, s4
	s_addc_u32 s49, s49, s5
	s_add_i32 s29, s29, s51
	v_lshl_add_u64 v[246:247], s[48:49], 0, v[144:145]
	s_mov_b32 m0, s29
	v_lshl_add_u64 v[248:249], s[48:49], 0, v[128:129]
	global_load_lds_dwordx4 v[246:247], off
	s_add_i32 m0, s29, 0x2000
	s_nop 0
	global_load_lds_dwordx4 v[248:249], off
	s_waitcnt vmcnt(6)
	s_barrier
	s_setprio 1
	v_mfma_f32_16x16x32_bf16 v[60:63], v[224:227], v[192:195], 0
	v_mfma_f32_16x16x32_bf16 v[52:55], v[232:235], v[192:195], 0
	v_mfma_f32_16x16x32_bf16 v[44:47], v[224:227], v[200:203], 0
	v_mfma_f32_16x16x32_bf16 v[36:39], v[232:235], v[200:203], 0
	v_mfma_f32_16x16x32_bf16 v[28:31], v[224:227], v[208:211], 0
	v_mfma_f32_16x16x32_bf16 v[20:23], v[232:235], v[208:211], 0
	v_mfma_f32_16x16x32_bf16 v[12:15], v[224:227], v[216:219], 0
	v_mfma_f32_16x16x32_bf16 v[4:7], v[232:235], v[216:219], 0
	v_mfma_f32_16x16x32_bf16 v[60:63], v[228:231], v[196:199], v[60:63]
	v_mfma_f32_16x16x32_bf16 v[52:55], v[236:239], v[196:199], v[52:55]
	v_mfma_f32_16x16x32_bf16 v[44:47], v[228:231], v[204:207], v[44:47]
	v_mfma_f32_16x16x32_bf16 v[36:39], v[236:239], v[204:207], v[36:39]
	v_mfma_f32_16x16x32_bf16 v[28:31], v[228:231], v[212:215], v[28:31]
	v_mfma_f32_16x16x32_bf16 v[20:23], v[236:239], v[212:215], v[20:23]
	v_mfma_f32_16x16x32_bf16 v[12:15], v[228:231], v[220:223], v[12:15]
	v_mfma_f32_16x16x32_bf16 v[4:7], v[236:239], v[220:223], v[4:7]
	s_setprio 0
	s_add_i32 s29, 0, 0x18000
	v_add_u32_e32 v188, s29, v141
	s_barrier
	ds_read_b128 v[160:163], v188
	ds_read_b128 v[164:167], v188 offset:1024
	ds_read_b128 v[168:171], v188 offset:2048
	ds_read_b128 v[188:191], v188 offset:3072
	s_add_u32 s8, s8, s4
	s_addc_u32 s9, s9, s5
	s_mov_b32 m0, s54
	v_lshl_add_u64 v[224:225], s[8:9], 0, v[132:133]
	ds_read_b128 v[192:195], v143 offset:32768
	ds_read_b128 v[196:199], v143 offset:33792
	ds_read_b128 v[200:203], v143 offset:34816
	ds_read_b128 v[204:207], v143 offset:35840
	ds_read_b128 v[208:211], v143 offset:36864
	ds_read_b128 v[212:215], v143 offset:37888
	ds_read_b128 v[216:219], v143 offset:38912
	ds_read_b128 v[220:223], v143 offset:39936
	global_load_lds_dwordx4 v[224:225], off
	v_lshl_add_u64 v[224:225], s[8:9], 0, v[130:131]
	s_mov_b32 m0, s55
	s_nop 0
	global_load_lds_dwordx4 v[224:225], off
	s_waitcnt lgkmcnt(8)
	s_barrier
	s_waitcnt lgkmcnt(0)
	s_setprio 1
	v_mfma_f32_16x16x32_bf16 v[120:123], v[160:163], v[192:195], v[120:123]
	v_mfma_f32_16x16x32_bf16 v[112:115], v[168:171], v[192:195], v[112:115]
	v_mfma_f32_16x16x32_bf16 v[104:107], v[160:163], v[200:203], v[104:107]
	v_mfma_f32_16x16x32_bf16 v[96:99], v[168:171], v[200:203], v[96:99]
	v_mfma_f32_16x16x32_bf16 v[88:91], v[160:163], v[208:211], v[88:91]
	v_mfma_f32_16x16x32_bf16 v[80:83], v[168:171], v[208:211], v[80:83]
	v_mfma_f32_16x16x32_bf16 v[72:75], v[160:163], v[216:219], v[72:75]
	v_mfma_f32_16x16x32_bf16 v[64:67], v[168:171], v[216:219], v[64:67]
	v_mfma_f32_16x16x32_bf16 v[120:123], v[164:167], v[196:199], v[120:123]
	v_mfma_f32_16x16x32_bf16 v[112:115], v[188:191], v[196:199], v[112:115]
	v_mfma_f32_16x16x32_bf16 v[104:107], v[164:167], v[204:207], v[104:107]
	v_mfma_f32_16x16x32_bf16 v[96:99], v[188:191], v[204:207], v[96:99]
	v_mfma_f32_16x16x32_bf16 v[88:91], v[164:167], v[212:215], v[88:91]
	v_mfma_f32_16x16x32_bf16 v[80:83], v[188:191], v[212:215], v[80:83]
	v_mfma_f32_16x16x32_bf16 v[72:75], v[164:167], v[220:223], v[72:75]
	v_mfma_f32_16x16x32_bf16 v[64:67], v[188:191], v[220:223], v[64:67]
	s_setprio 0
	s_barrier
	s_add_i32 s8, 0, 0x1c000
	s_add_i32 s9, s29, s51
	v_add_u32_e32 v236, s8, v141
	v_lshl_add_u64 v[138:139], v[138:139], 0, s[82:83]
	s_mov_b32 m0, s9
	ds_read_b128 v[224:227], v236
	ds_read_b128 v[228:231], v236 offset:1024
	ds_read_b128 v[232:235], v236 offset:2048
	ds_read_b128 v[236:239], v236 offset:3072
	global_load_lds_dwordx4 v[138:139], off
	v_lshl_add_u64 v[138:139], v[240:241], 0, s[82:83]
	s_add_i32 m0, s9, 0x2000
	s_nop 0
	global_load_lds_dwordx4 v[138:139], off
	s_barrier
	s_waitcnt lgkmcnt(0)
	s_setprio 1
	v_mfma_f32_16x16x32_bf16 v[124:127], v[224:227], v[192:195], v[124:127]
	v_mfma_f32_16x16x32_bf16 v[116:119], v[232:235], v[192:195], v[116:119]
	v_mfma_f32_16x16x32_bf16 v[108:111], v[224:227], v[200:203], v[108:111]
	v_mfma_f32_16x16x32_bf16 v[100:103], v[232:235], v[200:203], v[100:103]
	v_mfma_f32_16x16x32_bf16 v[92:95], v[224:227], v[208:211], v[92:95]
	v_mfma_f32_16x16x32_bf16 v[84:87], v[232:235], v[208:211], v[84:87]
	v_mfma_f32_16x16x32_bf16 v[76:79], v[224:227], v[216:219], v[76:79]
	v_mfma_f32_16x16x32_bf16 v[68:71], v[232:235], v[216:219], v[68:71]
	v_mfma_f32_16x16x32_bf16 v[124:127], v[228:231], v[196:199], v[124:127]
	v_mfma_f32_16x16x32_bf16 v[116:119], v[236:239], v[196:199], v[116:119]
	v_mfma_f32_16x16x32_bf16 v[108:111], v[228:231], v[204:207], v[108:111]
	v_mfma_f32_16x16x32_bf16 v[100:103], v[236:239], v[204:207], v[100:103]
	v_mfma_f32_16x16x32_bf16 v[92:95], v[228:231], v[212:215], v[92:95]
	v_mfma_f32_16x16x32_bf16 v[84:87], v[236:239], v[212:215], v[84:87]
	v_mfma_f32_16x16x32_bf16 v[76:79], v[228:231], v[220:223], v[76:79]
	v_mfma_f32_16x16x32_bf16 v[68:71], v[236:239], v[220:223], v[68:71]
	s_setprio 0
	s_mov_b32 m0, s57
	v_lshl_add_u64 v[138:139], v[242:243], 0, s[82:83]
	s_barrier
	ds_read_b128 v[192:195], v143 offset:49152
	ds_read_b128 v[196:199], v143 offset:50176
	ds_read_b128 v[200:203], v143 offset:51200
	ds_read_b128 v[204:207], v143 offset:52224
	ds_read_b128 v[208:211], v143 offset:53248
	ds_read_b128 v[212:215], v143 offset:54272
	ds_read_b128 v[216:219], v143 offset:55296
	ds_read_b128 v[220:223], v143 offset:56320
	global_load_lds_dwordx4 v[138:139], off
	v_lshl_add_u64 v[138:139], v[244:245], 0, s[82:83]
	s_mov_b32 m0, s58
	s_nop 0
	global_load_lds_dwordx4 v[138:139], off
	s_barrier
	s_waitcnt lgkmcnt(0)
	s_setprio 1
	v_mfma_f32_16x16x32_bf16 v[56:59], v[160:163], v[192:195], v[56:59]
	v_mfma_f32_16x16x32_bf16 v[48:51], v[168:171], v[192:195], v[48:51]
	v_mfma_f32_16x16x32_bf16 v[40:43], v[160:163], v[200:203], v[40:43]
	v_mfma_f32_16x16x32_bf16 v[32:35], v[168:171], v[200:203], v[32:35]
	v_mfma_f32_16x16x32_bf16 v[24:27], v[160:163], v[208:211], v[24:27]
	v_mfma_f32_16x16x32_bf16 v[16:19], v[168:171], v[208:211], v[16:19]
	v_mfma_f32_16x16x32_bf16 v[8:11], v[160:163], v[216:219], v[8:11]
	v_mfma_f32_16x16x32_bf16 v[0:3], v[168:171], v[216:219], v[0:3]
	v_mfma_f32_16x16x32_bf16 v[56:59], v[164:167], v[196:199], v[56:59]
	v_mfma_f32_16x16x32_bf16 v[48:51], v[188:191], v[196:199], v[48:51]
	v_mfma_f32_16x16x32_bf16 v[40:43], v[164:167], v[204:207], v[40:43]
	v_mfma_f32_16x16x32_bf16 v[32:35], v[188:191], v[204:207], v[32:35]
	v_mfma_f32_16x16x32_bf16 v[24:27], v[164:167], v[212:215], v[24:27]
	v_mfma_f32_16x16x32_bf16 v[16:19], v[188:191], v[212:215], v[16:19]
	v_mfma_f32_16x16x32_bf16 v[8:11], v[164:167], v[220:223], v[8:11]
	v_mfma_f32_16x16x32_bf16 v[0:3], v[188:191], v[220:223], v[0:3]
	s_setprio 0
	s_barrier
	s_add_i32 s8, s8, s51
	v_lshl_add_u64 v[138:139], v[246:247], 0, s[82:83]
	s_mov_b32 m0, s8
	s_nop 0
	global_load_lds_dwordx4 v[138:139], off
	v_lshl_add_u64 v[138:139], v[248:249], 0, s[82:83]
	s_add_i32 m0, s8, 0x2000
	s_nop 0
	global_load_lds_dwordx4 v[138:139], off
	s_waitcnt vmcnt(6)
	s_barrier
	s_setprio 1
	v_mfma_f32_16x16x32_bf16 v[60:63], v[224:227], v[192:195], v[60:63]
	v_mfma_f32_16x16x32_bf16 v[52:55], v[232:235], v[192:195], v[52:55]
	v_mfma_f32_16x16x32_bf16 v[44:47], v[224:227], v[200:203], v[44:47]
	v_mfma_f32_16x16x32_bf16 v[36:39], v[232:235], v[200:203], v[36:39]
	v_mfma_f32_16x16x32_bf16 v[28:31], v[224:227], v[208:211], v[28:31]
	v_mfma_f32_16x16x32_bf16 v[20:23], v[232:235], v[208:211], v[20:23]
	v_mfma_f32_16x16x32_bf16 v[12:15], v[224:227], v[216:219], v[12:15]
	v_mfma_f32_16x16x32_bf16 v[4:7], v[232:235], v[216:219], v[4:7]
	v_mfma_f32_16x16x32_bf16 v[60:63], v[228:231], v[196:199], v[60:63]
	v_mfma_f32_16x16x32_bf16 v[52:55], v[236:239], v[196:199], v[52:55]
	v_mfma_f32_16x16x32_bf16 v[44:47], v[228:231], v[204:207], v[44:47]
	v_mfma_f32_16x16x32_bf16 v[36:39], v[236:239], v[204:207], v[36:39]
	v_mfma_f32_16x16x32_bf16 v[28:31], v[228:231], v[212:215], v[28:31]
	v_mfma_f32_16x16x32_bf16 v[20:23], v[236:239], v[212:215], v[20:23]
	v_mfma_f32_16x16x32_bf16 v[12:15], v[228:231], v[220:223], v[12:15]
	v_mfma_f32_16x16x32_bf16 v[4:7], v[236:239], v[220:223], v[4:7]
	s_setprio 0
	s_add_u32 s10, s10, 0x100
	s_addc_u32 s11, s11, 0
	s_add_u32 s6, s6, 0x100
	s_addc_u32 s7, s7, 0
	s_cmp_ge_i32 s28, s56
	s_mov_b32 s8, s28
	s_barrier
	s_cbranch_scc0 .LBB0_1059
	s_branch .LBB0_1050

.LBB0_1130:
	s_andn2_b64 vcc, exec, s[4:5]
	s_cbranch_vccnz .Lcoldzero_7
	s_add_u32 s10, s6, 0x100
	s_addc_u32 s11, s7, 0
	s_add_u32 s6, s8, 0x80
	s_addc_u32 s7, s9, 0
	s_mov_b32 s8, 0
	s_add_i32 s28, s8, 2
	s_add_u32 s29, s6, 0x80
	s_addc_u32 s9, s7, 0
	s_add_i32 s71, 0, 0x10000
	v_add_u32_e32 v142, s71, v189
	ds_read_b128 v[134:137], v142
	ds_read_b128 v[138:141], v142 offset:1024
	ds_read_b128 v[160:163], v142 offset:2048
	ds_read_b128 v[164:167], v142 offset:3072
	s_cmp_eq_u32 s59, s8
	s_cselect_b32 s8, s40, s29
	s_cselect_b32 s9, s41, s9
	s_cselect_b32 s49, s43, s11
	s_cselect_b32 s48, s42, s10
	v_lshl_add_u64 v[142:143], s[6:7], 0, v[132:133]
	s_add_i32 m0, s52, 0xc000
	ds_read_b128 v[168:171], v191
	ds_read_b128 v[192:195], v191 offset:1024
	ds_read_b128 v[196:199], v191 offset:2048
	ds_read_b128 v[200:203], v191 offset:3072
	ds_read_b128 v[204:207], v191 offset:4096
	ds_read_b128 v[208:211], v191 offset:5120
	ds_read_b128 v[212:215], v191 offset:6144
	ds_read_b128 v[216:219], v191 offset:7168
	global_load_lds_dwordx4 v[142:143], off
	v_lshl_add_u64 v[142:143], s[6:7], 0, v[130:131]
	s_add_i32 m0, s52, 0xe000
	s_nop 0
	global_load_lds_dwordx4 v[142:143], off
	s_waitcnt lgkmcnt(8)
	s_barrier
	s_waitcnt lgkmcnt(0)
	s_setprio 1
	v_mfma_f32_16x16x32_bf16 v[124:127], v[134:137], v[168:171], 0
	v_mfma_f32_16x16x32_bf16 v[120:123], v[160:163], v[168:171], 0
	v_mfma_f32_16x16x32_bf16 v[108:111], v[134:137], v[196:199], 0
	v_mfma_f32_16x16x32_bf16 v[104:107], v[160:163], v[196:199], 0
	v_mfma_f32_16x16x32_bf16 v[92:95], v[134:137], v[204:207], 0
	v_mfma_f32_16x16x32_bf16 v[88:91], v[160:163], v[204:207], 0
	v_mfma_f32_16x16x32_bf16 v[76:79], v[134:137], v[212:215], 0
	v_mfma_f32_16x16x32_bf16 v[72:75], v[160:163], v[212:215], 0
	v_mfma_f32_16x16x32_bf16 v[124:127], v[138:141], v[192:195], v[124:127]
	v_mfma_f32_16x16x32_bf16 v[120:123], v[164:167], v[192:195], v[120:123]
	v_mfma_f32_16x16x32_bf16 v[108:111], v[138:141], v[200:203], v[108:111]
	v_mfma_f32_16x16x32_bf16 v[104:107], v[164:167], v[200:203], v[104:107]
	v_mfma_f32_16x16x32_bf16 v[92:95], v[138:141], v[208:211], v[92:95]
	v_mfma_f32_16x16x32_bf16 v[88:91], v[164:167], v[208:211], v[88:91]
	v_mfma_f32_16x16x32_bf16 v[76:79], v[138:141], v[216:219], v[76:79]
	v_mfma_f32_16x16x32_bf16 v[72:75], v[164:167], v[216:219], v[72:75]
	s_setprio 0
	s_barrier
	s_add_i32 s29, 0, 0x14000
	v_add_u32_e32 v142, s29, v189
	s_add_i32 s71, s71, s51
	ds_read_b128 v[220:223], v142
	ds_read_b128 v[224:227], v142 offset:1024
	ds_read_b128 v[228:231], v142 offset:2048
	ds_read_b128 v[232:235], v142 offset:3072
	v_lshl_add_u64 v[142:143], s[48:49], 0, v[144:145]
	s_mov_b32 m0, s71
	v_lshl_add_u64 v[236:237], s[48:49], 0, v[128:129]
	global_load_lds_dwordx4 v[142:143], off
	s_add_i32 m0, s71, 0x2000
	s_nop 0
	global_load_lds_dwordx4 v[236:237], off
	s_barrier
	s_waitcnt lgkmcnt(0)
	s_setprio 1
	v_mfma_f32_16x16x32_bf16 v[116:119], v[220:223], v[168:171], 0
	v_mfma_f32_16x16x32_bf16 v[112:115], v[228:231], v[168:171], 0
	v_mfma_f32_16x16x32_bf16 v[100:103], v[220:223], v[196:199], 0
	v_mfma_f32_16x16x32_bf16 v[96:99], v[228:231], v[196:199], 0
	v_mfma_f32_16x16x32_bf16 v[84:87], v[220:223], v[204:207], 0
	v_mfma_f32_16x16x32_bf16 v[80:83], v[228:231], v[204:207], 0
	v_mfma_f32_16x16x32_bf16 v[68:71], v[220:223], v[212:215], 0
	v_mfma_f32_16x16x32_bf16 v[64:67], v[228:231], v[212:215], 0
	v_mfma_f32_16x16x32_bf16 v[116:119], v[224:227], v[192:195], v[116:119]
	v_mfma_f32_16x16x32_bf16 v[112:115], v[232:235], v[192:195], v[112:115]
	v_mfma_f32_16x16x32_bf16 v[100:103], v[224:227], v[200:203], v[100:103]
	v_mfma_f32_16x16x32_bf16 v[96:99], v[232:235], v[200:203], v[96:99]
	v_mfma_f32_16x16x32_bf16 v[84:87], v[224:227], v[208:211], v[84:87]
	v_mfma_f32_16x16x32_bf16 v[80:83], v[232:235], v[208:211], v[80:83]
	v_mfma_f32_16x16x32_bf16 v[68:71], v[224:227], v[216:219], v[68:71]
	v_mfma_f32_16x16x32_bf16 v[64:67], v[232:235], v[216:219], v[64:67]
	s_setprio 0
	s_mov_b32 m0, s52
	v_lshl_add_u64 v[238:239], s[8:9], 0, v[144:145]
	s_barrier
	ds_read_b128 v[168:171], v191 offset:16384
	ds_read_b128 v[192:195], v191 offset:17408
	ds_read_b128 v[196:199], v191 offset:18432
	ds_read_b128 v[200:203], v191 offset:19456
	ds_read_b128 v[204:207], v191 offset:20480
	ds_read_b128 v[208:211], v191 offset:21504
	ds_read_b128 v[212:215], v191 offset:22528
	ds_read_b128 v[216:219], v191 offset:23552
	global_load_lds_dwordx4 v[238:239], off
	v_lshl_add_u64 v[240:241], s[8:9], 0, v[128:129]
	s_mov_b32 m0, s53
	s_nop 0
	global_load_lds_dwordx4 v[240:241], off
	s_barrier
	s_waitcnt lgkmcnt(0)
	s_setprio 1
	v_mfma_f32_16x16x32_bf16 v[60:63], v[134:137], v[168:171], 0
	v_mfma_f32_16x16x32_bf16 v[56:59], v[160:163], v[168:171], 0
	v_mfma_f32_16x16x32_bf16 v[44:47], v[134:137], v[196:199], 0
	v_mfma_f32_16x16x32_bf16 v[40:43], v[160:163], v[196:199], 0
	v_mfma_f32_16x16x32_bf16 v[28:31], v[134:137], v[204:207], 0
	v_mfma_f32_16x16x32_bf16 v[24:27], v[160:163], v[204:207], 0
	v_mfma_f32_16x16x32_bf16 v[12:15], v[134:137], v[212:215], 0
	v_mfma_f32_16x16x32_bf16 v[8:11], v[160:163], v[212:215], 0
	v_mfma_f32_16x16x32_bf16 v[60:63], v[138:141], v[192:195], v[60:63]
	v_mfma_f32_16x16x32_bf16 v[56:59], v[164:167], v[192:195], v[56:59]
	v_mfma_f32_16x16x32_bf16 v[44:47], v[138:141], v[200:203], v[44:47]
	v_mfma_f32_16x16x32_bf16 v[40:43], v[164:167], v[200:203], v[40:43]
	v_mfma_f32_16x16x32_bf16 v[28:31], v[138:141], v[208:211], v[28:31]
	v_mfma_f32_16x16x32_bf16 v[24:27], v[164:167], v[208:211], v[24:27]
	v_mfma_f32_16x16x32_bf16 v[12:15], v[138:141], v[216:219], v[12:15]
	v_mfma_f32_16x16x32_bf16 v[8:11], v[164:167], v[216:219], v[8:11]
	s_setprio 0
	s_barrier
	s_add_u32 s48, s48, s44
	s_addc_u32 s49, s49, s45
	s_add_i32 s29, s29, s51
	v_lshl_add_u64 v[242:243], s[48:49], 0, v[144:145]
	s_mov_b32 m0, s29
	v_lshl_add_u64 v[244:245], s[48:49], 0, v[128:129]
	global_load_lds_dwordx4 v[242:243], off
	s_add_i32 m0, s29, 0x2000
	s_nop 0
	global_load_lds_dwordx4 v[244:245], off
	s_waitcnt vmcnt(6)
	s_barrier
	s_setprio 1
	v_mfma_f32_16x16x32_bf16 v[52:55], v[220:223], v[168:171], 0
	v_mfma_f32_16x16x32_bf16 v[48:51], v[228:231], v[168:171], 0
	v_mfma_f32_16x16x32_bf16 v[36:39], v[220:223], v[196:199], 0
	v_mfma_f32_16x16x32_bf16 v[32:35], v[228:231], v[196:199], 0
	v_mfma_f32_16x16x32_bf16 v[20:23], v[220:223], v[204:207], 0
	v_mfma_f32_16x16x32_bf16 v[16:19], v[228:231], v[204:207], 0
	v_mfma_f32_16x16x32_bf16 v[4:7], v[220:223], v[212:215], 0
	v_mfma_f32_16x16x32_bf16 v[0:3], v[228:231], v[212:215], 0
	v_mfma_f32_16x16x32_bf16 v[52:55], v[224:227], v[192:195], v[52:55]
	v_mfma_f32_16x16x32_bf16 v[48:51], v[232:235], v[192:195], v[48:51]
	v_mfma_f32_16x16x32_bf16 v[36:39], v[224:227], v[200:203], v[36:39]
	v_mfma_f32_16x16x32_bf16 v[32:35], v[232:235], v[200:203], v[32:35]
	v_mfma_f32_16x16x32_bf16 v[20:23], v[224:227], v[208:211], v[20:23]
	v_mfma_f32_16x16x32_bf16 v[16:19], v[232:235], v[208:211], v[16:19]
	v_mfma_f32_16x16x32_bf16 v[4:7], v[224:227], v[216:219], v[4:7]
	v_mfma_f32_16x16x32_bf16 v[0:3], v[232:235], v[216:219], v[0:3]
	s_setprio 0
	s_add_i32 s29, 0, 0x18000
	v_add_u32_e32 v164, s29, v189
	s_barrier
	ds_read_b128 v[134:137], v164
	ds_read_b128 v[138:141], v164 offset:1024
	ds_read_b128 v[160:163], v164 offset:2048
	ds_read_b128 v[164:167], v164 offset:3072
	s_add_u32 s8, s8, s44
	s_addc_u32 s9, s9, s45
	s_mov_b32 m0, s54
	v_lshl_add_u64 v[220:221], s[8:9], 0, v[144:145]
	ds_read_b128 v[168:171], v191 offset:32768
	ds_read_b128 v[192:195], v191 offset:33792
	ds_read_b128 v[196:199], v191 offset:34816
	ds_read_b128 v[200:203], v191 offset:35840
	ds_read_b128 v[204:207], v191 offset:36864
	ds_read_b128 v[208:211], v191 offset:37888
	ds_read_b128 v[212:215], v191 offset:38912
	ds_read_b128 v[216:219], v191 offset:39936
	global_load_lds_dwordx4 v[220:221], off
	v_lshl_add_u64 v[220:221], s[8:9], 0, v[128:129]
	s_mov_b32 m0, s55
	s_nop 0
	global_load_lds_dwordx4 v[220:221], off
	s_waitcnt lgkmcnt(8)
	s_barrier
	s_waitcnt lgkmcnt(0)
	s_setprio 1
	v_mfma_f32_16x16x32_bf16 v[124:127], v[134:137], v[168:171], v[124:127]
	v_mfma_f32_16x16x32_bf16 v[120:123], v[160:163], v[168:171], v[120:123]
	v_mfma_f32_16x16x32_bf16 v[108:111], v[134:137], v[196:199], v[108:111]
	v_mfma_f32_16x16x32_bf16 v[104:107], v[160:163], v[196:199], v[104:107]
	v_mfma_f32_16x16x32_bf16 v[92:95], v[134:137], v[204:207], v[92:95]
	v_mfma_f32_16x16x32_bf16 v[88:91], v[160:163], v[204:207], v[88:91]
	v_mfma_f32_16x16x32_bf16 v[76:79], v[134:137], v[212:215], v[76:79]
	v_mfma_f32_16x16x32_bf16 v[72:75], v[160:163], v[212:215], v[72:75]
	v_mfma_f32_16x16x32_bf16 v[124:127], v[138:141], v[192:195], v[124:127]
	v_mfma_f32_16x16x32_bf16 v[120:123], v[164:167], v[192:195], v[120:123]
	v_mfma_f32_16x16x32_bf16 v[108:111], v[138:141], v[200:203], v[108:111]
	v_mfma_f32_16x16x32_bf16 v[104:107], v[164:167], v[200:203], v[104:107]
	v_mfma_f32_16x16x32_bf16 v[92:95], v[138:141], v[208:211], v[92:95]
	v_mfma_f32_16x16x32_bf16 v[88:91], v[164:167], v[208:211], v[88:91]
	v_mfma_f32_16x16x32_bf16 v[76:79], v[138:141], v[216:219], v[76:79]
	v_mfma_f32_16x16x32_bf16 v[72:75], v[164:167], v[216:219], v[72:75]
	s_setprio 0
	s_barrier
	s_add_i32 s8, 0, 0x1c000
	s_add_i32 s9, s29, s51
	v_add_u32_e32 v232, s8, v189
	v_lshl_add_u64 v[142:143], v[142:143], 0, s[82:83]
	s_mov_b32 m0, s9
	ds_read_b128 v[220:223], v232
	ds_read_b128 v[224:227], v232 offset:1024
	ds_read_b128 v[228:231], v232 offset:2048
	ds_read_b128 v[232:235], v232 offset:3072
	global_load_lds_dwordx4 v[142:143], off
	v_lshl_add_u64 v[142:143], v[236:237], 0, s[82:83]
	s_add_i32 m0, s9, 0x2000
	s_nop 0
	global_load_lds_dwordx4 v[142:143], off
	s_barrier
	s_waitcnt lgkmcnt(0)
	s_setprio 1
	v_mfma_f32_16x16x32_bf16 v[116:119], v[220:223], v[168:171], v[116:119]
	v_mfma_f32_16x16x32_bf16 v[112:115], v[228:231], v[168:171], v[112:115]
	v_mfma_f32_16x16x32_bf16 v[100:103], v[220:223], v[196:199], v[100:103]
	v_mfma_f32_16x16x32_bf16 v[96:99], v[228:231], v[196:199], v[96:99]
	v_mfma_f32_16x16x32_bf16 v[84:87], v[220:223], v[204:207], v[84:87]
	v_mfma_f32_16x16x32_bf16 v[80:83], v[228:231], v[204:207], v[80:83]
	v_mfma_f32_16x16x32_bf16 v[68:71], v[220:223], v[212:215], v[68:71]
	v_mfma_f32_16x16x32_bf16 v[64:67], v[228:231], v[212:215], v[64:67]
	v_mfma_f32_16x16x32_bf16 v[116:119], v[224:227], v[192:195], v[116:119]
	v_mfma_f32_16x16x32_bf16 v[112:115], v[232:235], v[192:195], v[112:115]
	v_mfma_f32_16x16x32_bf16 v[100:103], v[224:227], v[200:203], v[100:103]
	v_mfma_f32_16x16x32_bf16 v[96:99], v[232:235], v[200:203], v[96:99]
	v_mfma_f32_16x16x32_bf16 v[84:87], v[224:227], v[208:211], v[84:87]
	v_mfma_f32_16x16x32_bf16 v[80:83], v[232:235], v[208:211], v[80:83]
	v_mfma_f32_16x16x32_bf16 v[68:71], v[224:227], v[216:219], v[68:71]
	v_mfma_f32_16x16x32_bf16 v[64:67], v[232:235], v[216:219], v[64:67]
	s_setprio 0
	s_mov_b32 m0, s57
	v_lshl_add_u64 v[142:143], v[238:239], 0, s[82:83]
	s_barrier
	ds_read_b128 v[168:171], v191 offset:49152
	ds_read_b128 v[192:195], v191 offset:50176
	ds_read_b128 v[196:199], v191 offset:51200
	ds_read_b128 v[200:203], v191 offset:52224
	ds_read_b128 v[204:207], v191 offset:53248
	ds_read_b128 v[208:211], v191 offset:54272
	ds_read_b128 v[212:215], v191 offset:55296
	ds_read_b128 v[216:219], v191 offset:56320
	global_load_lds_dwordx4 v[142:143], off
	v_lshl_add_u64 v[142:143], v[240:241], 0, s[82:83]
	s_mov_b32 m0, s58
	s_nop 0
	global_load_lds_dwordx4 v[142:143], off
	s_barrier
	s_waitcnt lgkmcnt(0)
	s_setprio 1
	v_mfma_f32_16x16x32_bf16 v[60:63], v[134:137], v[168:171], v[60:63]
	v_mfma_f32_16x16x32_bf16 v[56:59], v[160:163], v[168:171], v[56:59]
	v_mfma_f32_16x16x32_bf16 v[44:47], v[134:137], v[196:199], v[44:47]
	v_mfma_f32_16x16x32_bf16 v[40:43], v[160:163], v[196:199], v[40:43]
	v_mfma_f32_16x16x32_bf16 v[28:31], v[134:137], v[204:207], v[28:31]
	v_mfma_f32_16x16x32_bf16 v[24:27], v[160:163], v[204:207], v[24:27]
	v_mfma_f32_16x16x32_bf16 v[12:15], v[134:137], v[212:215], v[12:15]
	v_mfma_f32_16x16x32_bf16 v[8:11], v[160:163], v[212:215], v[8:11]
	v_mfma_f32_16x16x32_bf16 v[60:63], v[138:141], v[192:195], v[60:63]
	v_mfma_f32_16x16x32_bf16 v[56:59], v[164:167], v[192:195], v[56:59]
	v_mfma_f32_16x16x32_bf16 v[44:47], v[138:141], v[200:203], v[44:47]
	v_mfma_f32_16x16x32_bf16 v[40:43], v[164:167], v[200:203], v[40:43]
	v_mfma_f32_16x16x32_bf16 v[28:31], v[138:141], v[208:211], v[28:31]
	v_mfma_f32_16x16x32_bf16 v[24:27], v[164:167], v[208:211], v[24:27]
	v_mfma_f32_16x16x32_bf16 v[12:15], v[138:141], v[216:219], v[12:15]
	v_mfma_f32_16x16x32_bf16 v[8:11], v[164:167], v[216:219], v[8:11]
	s_setprio 0
	s_barrier
	s_add_i32 s8, s8, s51
	v_lshl_add_u64 v[134:135], v[242:243], 0, s[82:83]
	s_mov_b32 m0, s8
	s_nop 0
	global_load_lds_dwordx4 v[134:135], off
	v_lshl_add_u64 v[134:135], v[244:245], 0, s[82:83]
	s_add_i32 m0, s8, 0x2000
	s_nop 0
	global_load_lds_dwordx4 v[134:135], off
	s_waitcnt vmcnt(6)
	s_barrier
	s_setprio 1
	v_mfma_f32_16x16x32_bf16 v[52:55], v[220:223], v[168:171], v[52:55]
	v_mfma_f32_16x16x32_bf16 v[48:51], v[228:231], v[168:171], v[48:51]
	v_mfma_f32_16x16x32_bf16 v[36:39], v[220:223], v[196:199], v[36:39]
	v_mfma_f32_16x16x32_bf16 v[32:35], v[228:231], v[196:199], v[32:35]
	v_mfma_f32_16x16x32_bf16 v[20:23], v[220:223], v[204:207], v[20:23]
	v_mfma_f32_16x16x32_bf16 v[16:19], v[228:231], v[204:207], v[16:19]
	v_mfma_f32_16x16x32_bf16 v[4:7], v[220:223], v[212:215], v[4:7]
	v_mfma_f32_16x16x32_bf16 v[0:3], v[228:231], v[212:215], v[0:3]
	v_mfma_f32_16x16x32_bf16 v[52:55], v[224:227], v[192:195], v[52:55]
	v_mfma_f32_16x16x32_bf16 v[48:51], v[232:235], v[192:195], v[48:51]
	v_mfma_f32_16x16x32_bf16 v[36:39], v[224:227], v[200:203], v[36:39]
	v_mfma_f32_16x16x32_bf16 v[32:35], v[232:235], v[200:203], v[32:35]
	v_mfma_f32_16x16x32_bf16 v[20:23], v[224:227], v[208:211], v[20:23]
	v_mfma_f32_16x16x32_bf16 v[16:19], v[232:235], v[208:211], v[16:19]
	v_mfma_f32_16x16x32_bf16 v[4:7], v[224:227], v[216:219], v[4:7]
	v_mfma_f32_16x16x32_bf16 v[0:3], v[232:235], v[216:219], v[0:3]
	s_setprio 0
	s_add_u32 s10, s10, 0x100
	s_addc_u32 s11, s11, 0
	s_add_u32 s6, s6, 0x100
	s_addc_u32 s7, s7, 0
	s_cmp_ge_i32 s28, s56
	s_mov_b32 s8, s28
	s_barrier
	s_cbranch_scc0 .LBB0_1132
	s_branch .LBB0_1119
